# grid barrier rewritten for barriers 2..17: one returning arrival atomic per WG, XCD leader flushes L2 then bumps 16 replicated release counters, every WG polls its XCD's copy; early L1 invalidate
# speedup vs baseline: 1.0183x; 1.0033x over previous
; __device__ __forceinline__ unsigned xb_ld(unsigned* p)              { return __hip_atomic_load(p, __ATOMIC_RELAXED, __HIP_MEMORY_SCOPE_AGENT); }
; __device__ __forceinline__ unsigned xb_add(unsigned* p, unsigned v) { return __hip_atomic_fetch_add(p, v, __ATOMIC_RELAXED, __HIP_MEMORY_SCOPE_AGENT); }
; #define XB_SPIN(cond, bar) do { unsigned _sp = 0; while (cond) { __builtin_amdgcn_s_sleep(1); \
;     if ((++_sp & 255u) == 0u) { if (xb_ld(&(bar)[XB_TMO])) break; if (_sp > XB_SPIN_CAP) { atomicAdd(&(bar)[XB_TMO], 1u); break; } } } } while (0)
; __device__ __forceinline__ void xcd_barrier(const XcdBarrier& b) {
;     asm volatile("s_waitcnt vmcnt(0)" ::: "memory");
;     __syncthreads();
;     if (threadIdx.x == 0) {
;         unsigned* bar = b.bar;
;         __builtin_amdgcn_s_waitcnt(0);
;         unsigned nloc = b.st[0], nx = b.st[1];
;         if (nloc == 0u) { xcd_barrier_complete(bar, b.x, nloc, nx); b.st[0] = nloc; b.st[1] = nx; }
;         const unsigned old = xb_add(&bar[XB_XSUB(b.x)], 1u);
;         const unsigned gen = old / nloc;
;         if (old + 1u == (gen + 1u) * nloc) {
;             __builtin_amdgcn_fence(__ATOMIC_RELEASE, "agent");
;             asm volatile("s_waitcnt vmcnt(0)" ::: "memory");
;             const unsigned og = xb_add(&bar[XB_TOP], 1u);
;             const unsigned tg = og / nx;
;             if (og + 1u == (tg + 1u) * nx) xb_add(&bar[XB_TOPGEN], 1u);
;             else XB_SPIN(xb_ld(&bar[XB_TOPGEN]) == tg, bar);
;             __builtin_amdgcn_fence(__ATOMIC_ACQUIRE, "agent");
;             xb_add(&bar[XB_XGEN(b.x)], 1u);
;             asm volatile("s_waitcnt vmcnt(0)" ::: "memory");
;         } else {
;             XB_SPIN(xb_ld(&bar[XB_XGEN(b.x)]) == gen, bar);
;             __builtin_amdgcn_fence(__ATOMIC_ACQUIRE, "agent");
;             asm volatile("s_waitcnt vmcnt(0)" ::: "memory");
;         }
;     }
;     __syncthreads();
; }
; __global__ void __launch_bounds__(NTHR, 2) fwd_megakernel(Args args) {
;     ...
;         if (even) {
.LBB0_161:
	s_getreg_b32 s4, hwreg(HW_REG_XCC_ID, 0, 4)
	s_waitcnt vmcnt(0)
	s_waitcnt vmcnt(0)
	s_barrier
	s_and_saveexec_b64 s[0:1], s[68:69]
	v_readlane_b32 s28, v254, 58
	s_xor_b64 s[0:1], exec, s[0:1]
	v_readlane_b32 s29, v254, 59
	s_cbranch_execz .LBB0_214
	v_readlane_b32 s2, v254, 42
	s_waitcnt vmcnt(0) expcnt(0) lgkmcnt(0)
	buffer_inv sc1
	s_and_b32 s10, s4, 15
	s_lshl_b32 s5, s10, 8
	v_mov_b32_e32 v0, s2
	ds_read_b32 v2, v0
	v_readlane_b32 s2, v254, 43
	s_add_u32 s12, s46, s5
	s_addc_u32 s13, s47, 0
	v_mov_b32_e32 v3, 1
	v_mov_b32_e32 v0, s2
	ds_read_b32 v6, v0
	v_mov_b32_e32 v5, 0x1400
	s_waitcnt lgkmcnt(0)
	global_atomic_add v3, v5, v3, s[12:13] sc0
	v_cvt_f32_u32_e32 v4, v2
	s_waitcnt vmcnt(0)
	v_mov_b32_e32 v5, v3
	v_sub_u32_e32 v3, 0, v2
	v_rcp_iflag_f32_e32 v4, v4
	s_nop 0
	v_mul_f32_e32 v4, 0x4f7ffffe, v4
	v_cvt_u32_f32_e32 v4, v4
	v_mul_lo_u32 v1, v3, v4
	v_mul_hi_u32 v1, v4, v1
	v_add_u32_e32 v1, v4, v1
	v_mul_hi_u32 v1, v5, v1
	v_mul_lo_u32 v3, v1, v2
	v_sub_u32_e32 v3, v5, v3
	v_add_u32_e32 v4, 1, v1
	v_cmp_ge_u32_e32 vcc, v3, v2
	s_nop 1
	v_cndmask_b32_e32 v1, v1, v4, vcc
	v_sub_u32_e32 v4, v3, v2
	v_cndmask_b32_e32 v3, v3, v4, vcc
	v_add_u32_e32 v4, 1, v1
	v_cmp_ge_u32_e32 vcc, v3, v2
	v_add_u32_e32 v3, 1, v5
	s_nop 0
	v_cndmask_b32_e32 v1, v1, v4, vcc
	v_mul_lo_u32 v4, v2, v1
	v_add_u32_e32 v2, v4, v2
	v_mul_lo_u32 v7, v1, v6
	v_cmp_ne_u32_e32 vcc, v3, v2
	s_mov_b32 s8, 0
	s_cbranch_vccnz .Lnb_loop_1
	buffer_wbl2 sc1
	v_mov_b32_e32 v8, 1
	v_mov_b32_e32 v9, 0x2404
	s_waitcnt vmcnt(0)
	global_atomic_add v9, v8, s[46:47]
	v_add_u32_e32 v9, 0x100, v9
	global_atomic_add v9, v8, s[46:47]
	v_add_u32_e32 v9, 0x100, v9
	global_atomic_add v9, v8, s[46:47]
	v_add_u32_e32 v9, 0x100, v9
	global_atomic_add v9, v8, s[46:47]
	v_add_u32_e32 v9, 0x100, v9
	global_atomic_add v9, v8, s[46:47]
	v_add_u32_e32 v9, 0x100, v9
	global_atomic_add v9, v8, s[46:47]
	v_add_u32_e32 v9, 0x100, v9
	global_atomic_add v9, v8, s[46:47]
	v_add_u32_e32 v9, 0x100, v9
	global_atomic_add v9, v8, s[46:47]
	v_add_u32_e32 v9, 0x100, v9
	global_atomic_add v9, v8, s[46:47]
	v_add_u32_e32 v9, 0x100, v9
	global_atomic_add v9, v8, s[46:47]
	v_add_u32_e32 v9, 0x100, v9
	global_atomic_add v9, v8, s[46:47]
	v_add_u32_e32 v9, 0x100, v9
	global_atomic_add v9, v8, s[46:47]
	v_add_u32_e32 v9, 0x100, v9
	global_atomic_add v9, v8, s[46:47]
	v_add_u32_e32 v9, 0x100, v9
	global_atomic_add v9, v8, s[46:47]
	v_add_u32_e32 v9, 0x100, v9
	global_atomic_add v9, v8, s[46:47]
	v_add_u32_e32 v9, 0x100, v9
	global_atomic_add v9, v8, s[46:47]
.Lnb_loop_1:
	s_sleep 1
	v_mov_b32_e32 v9, 0x2404
	global_load_dword v8, v9, s[12:13] sc1
	s_add_u32 s8, s8, 1
	s_cmp_gt_u32 s8, 0x4000
	s_cbranch_scc1 .Lnb_done_1
	s_waitcnt vmcnt(0)
	v_cmp_lt_u32_e32 vcc, v8, v7
	s_cbranch_vccnz .Lnb_loop_1
.Lnb_done_1:
	s_waitcnt vmcnt(0)
.LBB0_214:
	s_or_b64 exec, exec, s[0:1]
	v_readlane_b32 s0, v254, 61
	v_readlane_b32 s1, v254, 62
	s_xor_b64 s[0:1], s[0:1], -1
	s_and_b64 vcc, exec, s[0:1]
	v_readlane_b32 s0, v253, 42
	v_readlane_b32 s1, v253, 43
	s_mov_b64 s[6:7], -1
	s_waitcnt lgkmcnt(0)
	v_cndmask_b32_e64 v0, 0, 1, s[0:1]
	v_cmp_ne_u32_e64 s[24:25], 1, v0
	s_barrier
	s_cbranch_vccz .LBB0_393
	v_mov_b32_e32 v52, v186
	s_load_dword s66, s[70:71], 0x0
	v_writelane_b32 v254, s24, 63
	s_mov_b64 s[20:21], 0x1000
	s_and_b64 vcc, exec, s[24:25]
	v_writelane_b32 v255, s25, 0
	v_readfirstlane_b32 s0, v52
	s_mov_b64 s[22:23], 0x3c00
	s_mov_b64 s[24:25], 0x10000
	s_mov_b64 s[30:31], 0x1400
	s_mov_b64 s[34:35], 0x2000
	s_mov_b64 s[36:37], 0x2400
	s_mov_b64 s[54:55], 0x2800
	s_mov_b64 s[50:51], 0x2c00
	s_mov_b64 s[48:49], 0x1800
	s_mov_b64 s[56:57], 0x1c00
	s_mov_b64 s[58:59], 0x3800
	s_mov_b64 s[62:63], 0x3000
	s_cbranch_vccnz .LBB0_218
; DI void prep_odd(const Ctx& c, const Args& a) {
;     ...
;     float* gal = (float*)c.lds;
;     const int ch = c.tid, h = ch >> 7, d = ch & 127;
;     float wa[16];
; #pragma unroll
;     for (int r = 0; r < 16; ++r) wa[r] = a.in[8][r * 512 + ch];
;     const float ba = a.in[9][ch];
;     for (int cp = c.bid; cp < 512; cp += c.G) {
;         __syncthreads();
;         {
;             const int l31 = c.lane & 31, hi = c.lane >> 5;
;             const bf16* xn = (const bf16*)(a.ws + WS_XN) + (size_t)cp * 64 * 1024 + 128 * c.wave;
;             const bf16* w16 = (const bf16*)(a.ws + WS_WINO) + (size_t)3072 * 1024 + 128 * c.wave;
;             bf16x8 wf[8], xf[2][8];
; #pragma unroll
;             for (int kk = 0; kk < 8; ++kk) { wf[kk] = *(const bf16x8*)(w16 + (size_t)(l31 & 15) * 1024 + 16 * kk + 8 * hi);
;                 xf[0][kk] = *(const bf16x8*)(xn + (size_t)l31 * 1024 + 16 * kk + 8 * hi); xf[1][kk] = *(const bf16x8*)(xn + (size_t)(32 + l31) * 1024 + 16 * kk + 8 * hi); }
;             float* part = (float*)(c.lds + 4096) + c.wave * 1024;
	v_ashrrev_i32_e32 v53, 31, v52
	v_readlane_b32 s4, v253, 20
	v_lshlrev_b64 v[0:1], 2, v[52:53]
	v_readlane_b32 s6, v253, 22
	v_readlane_b32 s7, v253, 23
	v_readlane_b32 s5, v253, 21
	s_movk_i32 s1, 0x4000
	v_lshl_add_u64 v[2:3], s[6:7], 0, v[0:1]
	v_readlane_b32 s6, v253, 40
	v_readlane_b32 s7, v253, 41
	global_load_dword v102, v[2:3], off
	v_readlane_b32 s2, v253, 44
	v_lshl_add_u64 v[54:55], s[6:7], 0, v[0:1]
	v_lshl_add_u64 v[0:1], s[4:5], 0, v[0:1]
	v_add_co_u32_e32 v2, vcc, 0x7000, v0
	s_ashr_i32 s6, s0, 6
	s_nop 0
	v_addc_co_u32_e32 v3, vcc, 0, v1, vcc
	v_add_co_u32_e32 v4, vcc, 0x6000, v0
	s_movk_i32 s0, 0x50
	s_nop 0
	v_addc_co_u32_e32 v5, vcc, 0, v1, vcc
	v_add_co_u32_e32 v6, vcc, 0x5000, v0
	v_bfe_u32 v25, v52, 5, 1
	s_nop 0
	v_addc_co_u32_e32 v7, vcc, 0, v1, vcc
	v_add_co_u32_e32 v8, vcc, s1, v0
	v_and_b32_e32 v23, 31, v52
	s_nop 0
	v_addc_co_u32_e32 v9, vcc, 0, v1, vcc
	v_add_co_u32_e32 v10, vcc, 0x3000, v0
	v_lshrrev_b32_e32 v24, 5, v52
	s_nop 0
	v_addc_co_u32_e32 v11, vcc, 0, v1, vcc
	v_add_co_u32_e32 v12, vcc, s52, v0
	v_and_b32_e32 v32, 7, v52
	s_nop 0
	v_addc_co_u32_e32 v13, vcc, 0, v1, vcc
	v_add_co_u32_e32 v14, vcc, 0x1000, v0
	v_lshl_add_u32 v104, v52, 2, 0
	s_nop 0
	v_addc_co_u32_e32 v15, vcc, 0, v1, vcc
	global_load_dword v56, v[8:9], off offset:2048
	global_load_dword v59, v[10:11], off offset:2048
	global_load_dword v61, v[12:13], off offset:2048
	global_load_dword v58, v[14:15], off offset:2048
	global_load_dword v62, v[14:15], off
	global_load_dword v65, v[12:13], off
	global_load_dword v63, v[10:11], off
	global_load_dword v66, v[8:9], off
	global_load_dword v69, v[2:3], off offset:2048
	global_load_dword v57, v[4:5], off offset:2048
	global_load_dword v68, v[6:7], off offset:2048
	global_load_dword v70, v[6:7], off
	global_load_dword v67, v[4:5], off
	global_load_dword v71, v[2:3], off
	global_load_dword v60, v[0:1], off offset:2048
	global_load_dword v64, v[0:1], off
	v_lshlrev_b32_e32 v0, 4, v52
	v_bitop3_b32 v20, v0, s0, v194 bitop3:0x6c
	s_movk_i32 s0, 0x60
	v_bitop3_b32 v21, v0, s0, v194 bitop3:0x6c
	s_movk_i32 s0, 0x70
	v_bitop3_b32 v22, v0, s0, v0 bitop3:0xc
	s_lshl_b32 s0, s6, 7
	s_ashr_i32 s1, s0, 31
	s_lshl_b64 s[0:1], s[0:1], 1
	s_add_u32 s4, s82, s0
	s_addc_u32 s5, s83, s1
	v_and_b32_e32 v3, 0x70, v0
	v_bitop3_b32 v16, v0, 16, v194 bitop3:0x6c
	v_bitop3_b32 v17, v0, 32, v194 bitop3:0x6c
	v_bitop3_b32 v18, v0, 48, v194 bitop3:0x6c
	v_bitop3_b32 v19, v0, 64, v194 bitop3:0x6c
	s_add_u32 s0, s2, s0
	v_readlane_b32 s2, v253, 45
	v_lshlrev_b32_e32 v0, 11, v52
	s_addc_u32 s1, s2, s1
	v_and_b32_e32 v160, 0x7800, v0
	v_lshl_add_u64 v[0:1], s[0:1], 0, v[160:161]
	v_lshlrev_b32_e32 v160, 4, v25
	v_lshl_add_u64 v[72:73], v[0:1], 0, v[160:161]
	v_lshlrev_b32_e32 v0, 11, v23
	v_mov_b32_e32 v1, v161
	s_lshl_b32 s0, s6, 12
	v_lshl_add_u64 v[74:75], s[4:5], 0, v[0:1]
	s_add_i32 s0, s0, 0
	v_lshlrev_b32_e32 v0, 6, v23
	v_add3_u32 v103, s0, v0, v160
	v_add_u32_e32 v0, 0x200, v52
	v_ashrrev_i32_e32 v1, 31, v0
	v_add_u32_e32 v8, 0x800, v52
	v_lshlrev_b64 v[78:79], 4, v[0:1]
	v_ashrrev_i32_e32 v9, 31, v8
	v_ashrrev_i32_e32 v0, 3, v0
	v_lshlrev_b64 v[84:85], 4, v[8:9]
	v_add_u32_e32 v10, 0xa00, v52
	v_lshl_add_u32 v9, v0, 7, 0
	v_xor_b32_e32 v0, v0, v52
	v_add_u32_e32 v4, 0x400, v52
	v_ashrrev_i32_e32 v11, 31, v10
	v_lshlrev_b32_e32 v0, 4, v0
	v_ashrrev_i32_e32 v5, 31, v4
	v_lshlrev_b64 v[86:87], 4, v[10:11]
	v_and_b32_e32 v11, 0x70, v0
	v_ashrrev_i32_e32 v0, 3, v4
	v_lshlrev_b64 v[80:81], 4, v[4:5]
	v_add_u32_e32 v12, 0xc00, v52
	v_lshl_add_u32 v4, v0, 7, 0
	v_xor_b32_e32 v0, v0, v52
	v_add_u32_e32 v6, 0x600, v52
	v_ashrrev_i32_e32 v13, 31, v12
	v_lshlrev_b32_e32 v0, 4, v0
	v_ashrrev_i32_e32 v7, 31, v6
	v_lshlrev_b64 v[88:89], 4, v[12:13]
	v_and_b32_e32 v13, 0x70, v0
	v_ashrrev_i32_e32 v0, 3, v6
	v_lshlrev_b64 v[82:83], 4, v[6:7]
	v_add_u32_e32 v14, 0xe00, v52
	v_lshl_add_u32 v6, v0, 7, 0
	v_xor_b32_e32 v0, v0, v52
	v_ashrrev_i32_e32 v15, 31, v14
	v_lshlrev_b32_e32 v0, 4, v0
	v_lshlrev_b64 v[90:91], 4, v[14:15]
	v_and_b32_e32 v15, 0x70, v0
	v_ashrrev_i32_e32 v0, 3, v8
	v_lshl_add_u32 v8, v0, 7, 0
	v_xor_b32_e32 v0, v0, v52
	v_lshlrev_b32_e32 v0, 4, v0
	v_and_b32_e32 v27, 0x70, v0
	v_ashrrev_i32_e32 v0, 3, v10
	v_lshl_add_u32 v10, v0, 7, 0
	v_xor_b32_e32 v0, v0, v52
	v_lshlrev_b32_e32 v0, 4, v0
	v_and_b32_e32 v28, 0x70, v0
	v_ashrrev_i32_e32 v0, 3, v12
	v_lshl_add_u32 v12, v0, 7, 0
	v_xor_b32_e32 v0, v0, v52
	v_lshlrev_b32_e32 v0, 4, v0
	v_and_b32_e32 v29, 0x70, v0
	v_ashrrev_i32_e32 v0, 3, v14
	v_ashrrev_i32_e32 v1, 3, v52
	v_lshl_add_u32 v14, v0, 7, 0
	v_xor_b32_e32 v0, v0, v52
	v_lshl_add_u32 v5, v1, 7, 0
	v_xor_b32_e32 v1, v1, v52
	v_lshlrev_b32_e32 v0, 4, v0
	s_lshl_b32 s1, s6, 5
	v_lshlrev_b32_e32 v1, 4, v1
	v_and_b32_e32 v30, 0x70, v0
	v_lshl_or_b32 v0, v25, 2, s1
	v_and_b32_e32 v7, 0x70, v1
	v_ashrrev_i32_e32 v1, 31, v0
	v_readlane_b32 s4, v253, 58
	v_lshlrev_b64 v[0:1], 8, v[0:1]
	v_readlane_b32 s5, v253, 59
	v_lshlrev_b32_e32 v160, 1, v23
	s_add_i32 s0, 0, 0x10000
	v_lshl_add_u64 v[0:1], s[4:5], 0, v[0:1]
	v_lshl_add_u64 v[92:93], v[0:1], 0, v[160:161]
	v_bitop3_b32 v0, v24, v32, 1 bitop3:0x6c
	v_lshlrev_b32_e32 v106, 4, v0
	v_bitop3_b32 v0, v25, v32, 2 bitop3:0x36
	v_lshlrev_b32_e32 v107, 4, v0
	v_bitop3_b32 v0, v25, v32, 4 bitop3:0x36
	v_lshlrev_b32_e32 v2, 3, v25
	v_lshl_add_u32 v26, v52, 7, s0
	v_or_b32_e32 v31, s1, v23
	v_lshlrev_b32_e32 v108, 4, v0
	v_bitop3_b32 v0, v25, v32, 6 bitop3:0x36
	v_lshlrev_b64 v[76:77], 4, v[52:53]
	v_lshl_add_u32 v105, v31, 7, 0
	v_lshlrev_b32_e32 v109, 4, v0
	v_lshl_add_u32 v110, v23, 7, s0
	v_lshlrev_b32_e32 v160, 1, v2
	v_add_u32_e32 v111, v26, v3
	v_add_u32_e32 v112, v26, v16
	v_add_u32_e32 v113, v26, v17
	v_add_u32_e32 v114, v26, v18
	v_add_u32_e32 v115, v26, v19
	v_add_u32_e32 v116, v26, v20
	v_add_u32_e32 v117, v26, v21
	v_add_u32_e32 v118, v26, v22
	v_add_u32_e32 v119, v5, v7
	v_add_u32_e32 v120, v9, v11
	v_add_u32_e32 v121, v4, v13
	v_add_u32_e32 v122, v6, v15
	v_add_u32_e32 v123, v8, v27
	v_add_u32_e32 v124, v10, v28
	v_add_u32_e32 v125, v12, v29
	v_add_u32_e32 v126, v14, v30
	s_mov_b32 s0, s90
	v_readlane_b32 s8, v253, 24
	v_readlane_b32 s9, v253, 25
	v_readlane_b32 s10, v253, 26
	v_readlane_b32 s11, v253, 27
	v_readlane_b32 s12, v253, 28
	v_readlane_b32 s13, v253, 29
	v_readlane_b32 s14, v253, 30
	v_readlane_b32 s15, v253, 31
	v_readlane_b32 s16, v253, 32
	v_readlane_b32 s17, v253, 33
	v_readlane_b32 s18, v253, 34
	v_readlane_b32 s19, v253, 35

; __device__ __forceinline__ unsigned xb_ld(unsigned* p)              { return __hip_atomic_load(p, __ATOMIC_RELAXED, __HIP_MEMORY_SCOPE_AGENT); }
; __device__ __forceinline__ unsigned xb_add(unsigned* p, unsigned v) { return __hip_atomic_fetch_add(p, v, __ATOMIC_RELAXED, __HIP_MEMORY_SCOPE_AGENT); }
; #define XB_SPIN(cond, bar) do { unsigned _sp = 0; while (cond) { __builtin_amdgcn_s_sleep(1); \
;     if ((++_sp & 255u) == 0u) { if (xb_ld(&(bar)[XB_TMO])) break; if (_sp > XB_SPIN_CAP) { atomicAdd(&(bar)[XB_TMO], 1u); break; } } } } while (0)
; __device__ __forceinline__ void xcd_barrier(const XcdBarrier& b) {
;     asm volatile("s_waitcnt vmcnt(0)" ::: "memory");
;     __syncthreads();
;     if (threadIdx.x == 0) {
;         unsigned* bar = b.bar;
;         __builtin_amdgcn_s_waitcnt(0);
;         unsigned nloc = b.st[0], nx = b.st[1];
;         if (nloc == 0u) { xcd_barrier_complete(bar, b.x, nloc, nx); b.st[0] = nloc; b.st[1] = nx; }
;         const unsigned old = xb_add(&bar[XB_XSUB(b.x)], 1u);
;         const unsigned gen = old / nloc;
;         if (old + 1u == (gen + 1u) * nloc) {
;             __builtin_amdgcn_fence(__ATOMIC_RELEASE, "agent");
;             asm volatile("s_waitcnt vmcnt(0)" ::: "memory");
;             const unsigned og = xb_add(&bar[XB_TOP], 1u);
;             const unsigned tg = og / nx;
;             if (og + 1u == (tg + 1u) * nx) xb_add(&bar[XB_TOPGEN], 1u);
;             else XB_SPIN(xb_ld(&bar[XB_TOPGEN]) == tg, bar);
;             __builtin_amdgcn_fence(__ATOMIC_ACQUIRE, "agent");
;             xb_add(&bar[XB_XGEN(b.x)], 1u);
;             asm volatile("s_waitcnt vmcnt(0)" ::: "memory");
;         } else {
;             XB_SPIN(xb_ld(&bar[XB_XGEN(b.x)]) == gen, bar);
;             __builtin_amdgcn_fence(__ATOMIC_ACQUIRE, "agent");
;             asm volatile("s_waitcnt vmcnt(0)" ::: "memory");
;         }
;     }
;     __syncthreads();
; }
.LBB0_218:
	s_getreg_b32 s4, hwreg(HW_REG_XCC_ID, 0, 4)
	s_waitcnt vmcnt(0)
	s_mov_b64 s[48:49], 0x3000
	s_mov_b64 s[62:63], 0x3800
	s_mov_b64 s[96:97], 0x1c00
	s_mov_b64 s[50:51], 0x2c00
	s_mov_b64 s[58:59], 0x2800
	s_mov_b64 s[56:57], 0x2400
	s_mov_b64 s[54:55], 0x2000
	s_waitcnt lgkmcnt(0)
	s_barrier
	s_and_saveexec_b64 s[0:1], s[68:69]
	s_cbranch_execz .LBB0_270
	v_readlane_b32 s2, v254, 42
	s_waitcnt vmcnt(0) expcnt(0) lgkmcnt(0)
	buffer_inv sc1
	s_and_b32 s10, s4, 15
	s_lshl_b32 s5, s10, 8
	v_mov_b32_e32 v0, s2
	ds_read_b32 v2, v0
	v_readlane_b32 s2, v254, 43
	s_add_u32 s12, s46, s5
	s_addc_u32 s13, s47, 0
	v_mov_b32_e32 v3, 1
	v_mov_b32_e32 v0, s2
	ds_read_b32 v6, v0
	v_mov_b32_e32 v5, 0x1400
	s_waitcnt lgkmcnt(0)
	global_atomic_add v3, v5, v3, s[12:13] sc0
	v_cvt_f32_u32_e32 v4, v2
	s_waitcnt vmcnt(0)
	v_mov_b32_e32 v5, v3
	v_sub_u32_e32 v3, 0, v2
	v_rcp_iflag_f32_e32 v4, v4
	s_nop 0
	v_mul_f32_e32 v4, 0x4f7ffffe, v4
	v_cvt_u32_f32_e32 v4, v4
	v_mul_lo_u32 v1, v3, v4
	v_mul_hi_u32 v1, v4, v1
	v_add_u32_e32 v1, v4, v1
	v_mul_hi_u32 v1, v5, v1
	v_mul_lo_u32 v3, v1, v2
	v_sub_u32_e32 v3, v5, v3
	v_add_u32_e32 v4, 1, v1
	v_cmp_ge_u32_e32 vcc, v3, v2
	s_nop 1
	v_cndmask_b32_e32 v1, v1, v4, vcc
	v_sub_u32_e32 v4, v3, v2
	v_cndmask_b32_e32 v3, v3, v4, vcc
	v_add_u32_e32 v4, 1, v1
	v_cmp_ge_u32_e32 vcc, v3, v2
	v_add_u32_e32 v3, 1, v5
	s_nop 0
	v_cndmask_b32_e32 v1, v1, v4, vcc
	v_mul_lo_u32 v4, v2, v1
	v_add_u32_e32 v2, v4, v2
	v_mul_lo_u32 v7, v1, v6
	v_cmp_ne_u32_e32 vcc, v3, v2
	s_mov_b32 s8, 0
	s_cbranch_vccnz .Lnb_loop_2
	buffer_wbl2 sc1
	v_mov_b32_e32 v8, 1
	v_mov_b32_e32 v9, 0x2404
	s_waitcnt vmcnt(0)
	global_atomic_add v9, v8, s[46:47]
	v_add_u32_e32 v9, 0x100, v9
	global_atomic_add v9, v8, s[46:47]
	v_add_u32_e32 v9, 0x100, v9
	global_atomic_add v9, v8, s[46:47]
	v_add_u32_e32 v9, 0x100, v9
	global_atomic_add v9, v8, s[46:47]
	v_add_u32_e32 v9, 0x100, v9
	global_atomic_add v9, v8, s[46:47]
	v_add_u32_e32 v9, 0x100, v9
	global_atomic_add v9, v8, s[46:47]
	v_add_u32_e32 v9, 0x100, v9
	global_atomic_add v9, v8, s[46:47]
	v_add_u32_e32 v9, 0x100, v9
	global_atomic_add v9, v8, s[46:47]
	v_add_u32_e32 v9, 0x100, v9
	global_atomic_add v9, v8, s[46:47]
	v_add_u32_e32 v9, 0x100, v9
	global_atomic_add v9, v8, s[46:47]
	v_add_u32_e32 v9, 0x100, v9
	global_atomic_add v9, v8, s[46:47]
	v_add_u32_e32 v9, 0x100, v9
	global_atomic_add v9, v8, s[46:47]
	v_add_u32_e32 v9, 0x100, v9
	global_atomic_add v9, v8, s[46:47]
	v_add_u32_e32 v9, 0x100, v9
	global_atomic_add v9, v8, s[46:47]
	v_add_u32_e32 v9, 0x100, v9
	global_atomic_add v9, v8, s[46:47]
	v_add_u32_e32 v9, 0x100, v9
	global_atomic_add v9, v8, s[46:47]

; DI float ex2(float x) { return __builtin_amdgcn_exp2f(x); }
; __device__ __forceinline__ unsigned xb_ld(unsigned* p)              { return __hip_atomic_load(p, __ATOMIC_RELAXED, __HIP_MEMORY_SCOPE_AGENT); }
; __device__ __forceinline__ unsigned xb_add(unsigned* p, unsigned v) { return __hip_atomic_fetch_add(p, v, __ATOMIC_RELAXED, __HIP_MEMORY_SCOPE_AGENT); }
; #define XB_SPIN(cond, bar) do { unsigned _sp = 0; while (cond) { __builtin_amdgcn_s_sleep(1); \
;     if ((++_sp & 255u) == 0u) { if (xb_ld(&(bar)[XB_TMO])) break; if (_sp > XB_SPIN_CAP) { atomicAdd(&(bar)[XB_TMO], 1u); break; } } } } while (0)
; template <int DV, bool GLA, bool DRY = false> DI void la2(const Ctx& c, bf16* ST, const float* DEC) {
;     const int ntask = 8 * DV * 64;
;     typedef float f32x2 __attribute__((ext_vector_type(2)));
;     for (int task = c.bid * NTHR + c.tid; task < ntask; task += c.G * NTHR) {
;         const int dp = task & 63, e = (task >> 6) % DV, bh = task / (64 * DV), b = bh >> 2, h = bh & 3;
;         float s0 = 0.f, s1 = 0.f;
;         f32x2 dc; { const float g = ex2(64.f * lgam2_of(h)); dc = (f32x2){g, g}; }
;         unsigned* base = (unsigned*)(ST + ((size_t)(b * 256) * 4 + h) * DV * 128 + (size_t)e * 128 + 2 * dp);
;         const size_t ustride = (size_t)4 * DV * 128 / 2;
;         const float* dbase = DEC + (size_t)(b * 256) * 512 + h * 128 + 2 * dp;
; __device__ __forceinline__ void xcd_barrier(const XcdBarrier& b) {
;     ...
;         const unsigned old = xb_add(&bar[XB_XSUB(b.x)], 1u);
;         const unsigned gen = old / nloc;
;         if (old + 1u == (gen + 1u) * nloc) {
;             __builtin_amdgcn_fence(__ATOMIC_RELEASE, "agent");
;             asm volatile("s_waitcnt vmcnt(0)" ::: "memory");
;             const unsigned og = xb_add(&bar[XB_TOP], 1u);
;             const unsigned tg = og / nx;
;             if (og + 1u == (tg + 1u) * nx) xb_add(&bar[XB_TOPGEN], 1u);
;             else XB_SPIN(xb_ld(&bar[XB_TOPGEN]) == tg, bar);
;             __builtin_amdgcn_fence(__ATOMIC_ACQUIRE, "agent");
;             xb_add(&bar[XB_XGEN(b.x)], 1u);
;             asm volatile("s_waitcnt vmcnt(0)" ::: "memory");
;         } else {
;             XB_SPIN(xb_ld(&bar[XB_XGEN(b.x)]) == gen, bar);
;             __builtin_amdgcn_fence(__ATOMIC_ACQUIRE, "agent");
;             asm volatile("s_waitcnt vmcnt(0)" ::: "memory");
;         }
;     }
;     __syncthreads();
; }
.Lnb_done_2:
	s_waitcnt vmcnt(0)
.LBB0_270:
	s_or_b64 exec, exec, s[0:1]
	s_waitcnt lgkmcnt(0)
	v_mov_b32_e32 v0, v186
	v_readlane_b32 s0, v254, 60
	s_barrier
	s_nop 0
	v_add_u32_e32 v134, s0, v0
	s_mov_b32 s0, 0x20000
	v_cmp_gt_i32_e32 vcc, s0, v134
	s_and_saveexec_b64 s[0:1], vcc
	s_cbranch_execz .LBB0_275
	v_readlane_b32 s2, v254, 33
	s_lshl_b32 s4, s66, 9
	s_lshl_b32 s5, s66, 10
	v_lshl_add_u32 v135, v0, 1, s2
	s_mov_b64 s[6:7], 0

; __device__ __forceinline__ unsigned xb_ld(unsigned* p)              { return __hip_atomic_load(p, __ATOMIC_RELAXED, __HIP_MEMORY_SCOPE_AGENT); }
; __device__ __forceinline__ unsigned xb_add(unsigned* p, unsigned v) { return __hip_atomic_fetch_add(p, v, __ATOMIC_RELAXED, __HIP_MEMORY_SCOPE_AGENT); }
; #define XB_SPIN(cond, bar) do { unsigned _sp = 0; while (cond) { __builtin_amdgcn_s_sleep(1); \
;     if ((++_sp & 255u) == 0u) { if (xb_ld(&(bar)[XB_TMO])) break; if (_sp > XB_SPIN_CAP) { atomicAdd(&(bar)[XB_TMO], 1u); break; } } } } while (0)
; __device__ __forceinline__ void xcd_barrier(const XcdBarrier& b) {
;     asm volatile("s_waitcnt vmcnt(0)" ::: "memory");
;     __syncthreads();
;     if (threadIdx.x == 0) {
;         unsigned* bar = b.bar;
;         __builtin_amdgcn_s_waitcnt(0);
;         unsigned nloc = b.st[0], nx = b.st[1];
;         if (nloc == 0u) { xcd_barrier_complete(bar, b.x, nloc, nx); b.st[0] = nloc; b.st[1] = nx; }
;         const unsigned old = xb_add(&bar[XB_XSUB(b.x)], 1u);
;         const unsigned gen = old / nloc;
;         if (old + 1u == (gen + 1u) * nloc) {
;             __builtin_amdgcn_fence(__ATOMIC_RELEASE, "agent");
;             asm volatile("s_waitcnt vmcnt(0)" ::: "memory");
;             const unsigned og = xb_add(&bar[XB_TOP], 1u);
;             const unsigned tg = og / nx;
;             if (og + 1u == (tg + 1u) * nx) xb_add(&bar[XB_TOPGEN], 1u);
;             else XB_SPIN(xb_ld(&bar[XB_TOPGEN]) == tg, bar);
;             __builtin_amdgcn_fence(__ATOMIC_ACQUIRE, "agent");
;             xb_add(&bar[XB_XGEN(b.x)], 1u);
;             asm volatile("s_waitcnt vmcnt(0)" ::: "memory");
;         } else {
;             XB_SPIN(xb_ld(&bar[XB_XGEN(b.x)]) == gen, bar);
;             __builtin_amdgcn_fence(__ATOMIC_ACQUIRE, "agent");
;             asm volatile("s_waitcnt vmcnt(0)" ::: "memory");
;         }
;     }
;     __syncthreads();
; }
.LBB0_275:
	s_or_b64 exec, exec, s[0:1]
	s_getreg_b32 s4, hwreg(HW_REG_XCC_ID, 0, 4)
	s_waitcnt vmcnt(0)
	s_barrier
	s_and_saveexec_b64 s[0:1], s[68:69]
	s_cbranch_execz .LBB0_327
	v_readlane_b32 s2, v254, 42
	s_waitcnt vmcnt(0) expcnt(0) lgkmcnt(0)
	buffer_inv sc1
	s_and_b32 s10, s4, 15
	s_lshl_b32 s5, s10, 8
	v_mov_b32_e32 v0, s2
	ds_read_b32 v2, v0
	v_readlane_b32 s2, v254, 43
	s_add_u32 s12, s46, s5
	s_addc_u32 s13, s47, 0
	v_mov_b32_e32 v3, 1
	v_mov_b32_e32 v0, s2
	ds_read_b32 v6, v0
	v_mov_b32_e32 v5, 0x1400
	s_waitcnt lgkmcnt(0)
	global_atomic_add v3, v5, v3, s[12:13] sc0
	v_cvt_f32_u32_e32 v4, v2
	s_waitcnt vmcnt(0)
	v_mov_b32_e32 v5, v3
	v_sub_u32_e32 v3, 0, v2
	v_rcp_iflag_f32_e32 v4, v4
	s_nop 0
	v_mul_f32_e32 v4, 0x4f7ffffe, v4
	v_cvt_u32_f32_e32 v4, v4
	v_mul_lo_u32 v1, v3, v4
	v_mul_hi_u32 v1, v4, v1
	v_add_u32_e32 v1, v4, v1
	v_mul_hi_u32 v1, v5, v1
	v_mul_lo_u32 v3, v1, v2
	v_sub_u32_e32 v3, v5, v3
	v_add_u32_e32 v4, 1, v1
	v_cmp_ge_u32_e32 vcc, v3, v2
	s_nop 1
	v_cndmask_b32_e32 v1, v1, v4, vcc
	v_sub_u32_e32 v4, v3, v2
	v_cndmask_b32_e32 v3, v3, v4, vcc
	v_add_u32_e32 v4, 1, v1
	v_cmp_ge_u32_e32 vcc, v3, v2
	v_add_u32_e32 v3, 1, v5
	s_nop 0
	v_cndmask_b32_e32 v1, v1, v4, vcc
	v_mul_lo_u32 v4, v2, v1
	v_add_u32_e32 v2, v4, v2
	v_mul_lo_u32 v7, v1, v6
	v_cmp_ne_u32_e32 vcc, v3, v2
	s_mov_b32 s8, 0
	s_cbranch_vccnz .Lnb_loop_3
	buffer_wbl2 sc1
	v_mov_b32_e32 v8, 1
	v_mov_b32_e32 v9, 0x2404
	s_waitcnt vmcnt(0)
	global_atomic_add v9, v8, s[46:47]
	v_add_u32_e32 v9, 0x100, v9
	global_atomic_add v9, v8, s[46:47]
	v_add_u32_e32 v9, 0x100, v9
	global_atomic_add v9, v8, s[46:47]
	v_add_u32_e32 v9, 0x100, v9
	global_atomic_add v9, v8, s[46:47]
	v_add_u32_e32 v9, 0x100, v9
	global_atomic_add v9, v8, s[46:47]
	v_add_u32_e32 v9, 0x100, v9
	global_atomic_add v9, v8, s[46:47]
	v_add_u32_e32 v9, 0x100, v9
	global_atomic_add v9, v8, s[46:47]
	v_add_u32_e32 v9, 0x100, v9
	global_atomic_add v9, v8, s[46:47]
	v_add_u32_e32 v9, 0x100, v9
	global_atomic_add v9, v8, s[46:47]
	v_add_u32_e32 v9, 0x100, v9
	global_atomic_add v9, v8, s[46:47]
	v_add_u32_e32 v9, 0x100, v9
	global_atomic_add v9, v8, s[46:47]
	v_add_u32_e32 v9, 0x100, v9
	global_atomic_add v9, v8, s[46:47]
	v_add_u32_e32 v9, 0x100, v9
	global_atomic_add v9, v8, s[46:47]
	v_add_u32_e32 v9, 0x100, v9
	global_atomic_add v9, v8, s[46:47]
	v_add_u32_e32 v9, 0x100, v9
	global_atomic_add v9, v8, s[46:47]
	v_add_u32_e32 v9, 0x100, v9
	global_atomic_add v9, v8, s[46:47]

; __device__ __forceinline__ unsigned xb_ld(unsigned* p)              { return __hip_atomic_load(p, __ATOMIC_RELAXED, __HIP_MEMORY_SCOPE_AGENT); }
; __device__ __forceinline__ unsigned xb_add(unsigned* p, unsigned v) { return __hip_atomic_fetch_add(p, v, __ATOMIC_RELAXED, __HIP_MEMORY_SCOPE_AGENT); }
; template <int DV> DI void la3(const Ctx& c, const bf16* __restrict__ QT, const bf16* __restrict__ KT, const bf16* __restrict__ VT, const bf16* __restrict__ ST, const float* __restrict__ gain, const bf16* __restrict__ gate, int gate_ld, bf16* __restrict__ OUT, int out_col0) {
;     constexpr int NP = (DV / 32) * 2 / 8, NEB = DV / 32;
;     const int l31 = c.lane & 31, hi = c.lane >> 5;
;     unsigned char* QL = c.lds; unsigned char* KL = c.lds + 16384; unsigned char* VL = c.lds + 32768; unsigned char* SL = c.lds + 65536;
;     bf16* Al = (bf16*)(c.lds + 131072);
;     float* SS = (float*)(c.lds + 131072 + 9216);
;     const int eb = (c.wave * NP) >> 1;
;     const int ib1 = c.wave >> 1, jb1 = c.wave & 1;
;     f32x4 gn[4];
; #pragma unroll
;     for (int g = 0; g < 4; ++g) gn[g] = *(const f32x4*)(gain + 32 * eb + 8 * g + 4 * hi);
;     ...
;     La3Stage<DV> stg;
;     if (c.bid < 2048) la3_issue<DV>(stg, QT, KT, VT, ST, c.bid, c.tid);
; __device__ __forceinline__ void xcd_barrier(const XcdBarrier& b) {
;     ...
;         const unsigned old = xb_add(&bar[XB_XSUB(b.x)], 1u);
;         const unsigned gen = old / nloc;
;         if (old + 1u == (gen + 1u) * nloc) {
;             __builtin_amdgcn_fence(__ATOMIC_RELEASE, "agent");
;             asm volatile("s_waitcnt vmcnt(0)" ::: "memory");
;             const unsigned og = xb_add(&bar[XB_TOP], 1u);
;             const unsigned tg = og / nx;
;             if (og + 1u == (tg + 1u) * nx) xb_add(&bar[XB_TOPGEN], 1u);
;             else XB_SPIN(xb_ld(&bar[XB_TOPGEN]) == tg, bar);
;             __builtin_amdgcn_fence(__ATOMIC_ACQUIRE, "agent");
;             xb_add(&bar[XB_XGEN(b.x)], 1u);
;             asm volatile("s_waitcnt vmcnt(0)" ::: "memory");
;         } else {
;             XB_SPIN(xb_ld(&bar[XB_XGEN(b.x)]) == gen, bar);
;             __builtin_amdgcn_fence(__ATOMIC_ACQUIRE, "agent");
;             asm volatile("s_waitcnt vmcnt(0)" ::: "memory");
;         }
;     }
;     __syncthreads();
; }
.Lnb_done_3:
	s_waitcnt vmcnt(0)
.LBB0_327:
	s_or_b64 exec, exec, s[0:1]
	v_readlane_b32 s0, v253, 46
	s_waitcnt lgkmcnt(0)
	v_mov_b32_e32 v0, v186
	v_readlane_b32 s1, v253, 47
	s_barrier
	s_and_b64 vcc, exec, s[0:1]
	v_readfirstlane_b32 s8, v0
	s_cbranch_vccz .LBB0_339
	s_ashr_i32 s0, s8, 6
	s_lshl_b32 s4, s0, 5
	s_ashr_i32 s5, s4, 31
	v_readlane_b32 s12, v253, 20
	s_and_b32 s1, s0, 1
	s_lshl_b64 s[4:5], s[4:5], 2
	v_readlane_b32 s16, v253, 24
	v_readlane_b32 s17, v253, 25
	s_add_u32 s4, s16, s4
	v_bfe_u32 v26, v0, 5, 1
	s_addc_u32 s5, s17, s5
	v_lshlrev_b32_e32 v28, 4, v26
	global_load_dwordx4 v[32:35], v28, s[4:5] offset:96
	global_load_dwordx4 v[36:39], v28, s[4:5] offset:64
	global_load_dwordx4 v[40:43], v28, s[4:5] offset:32
	global_load_dwordx4 v[44:47], v28, s[4:5]
	v_lshlrev_b32_e32 v1, 4, v0
	v_readlane_b32 s4, v253, 52
	v_and_b32_e32 v160, 0xf0, v1
	v_readlane_b32 s5, v253, 53
	v_ashrrev_i32_e32 v8, 4, v0
	v_ashrrev_i32_e32 v9, 31, v8
	v_lshl_add_u64 v[4:5], s[4:5], 0, v[160:161]
	v_readlane_b32 s4, v253, 54
	v_readlane_b32 s5, v253, 55
	v_lshlrev_b64 v[128:129], 9, v[8:9]
	v_ashrrev_i32_e32 v1, 31, v0
	v_lshl_add_u64 v[6:7], s[4:5], 0, v[160:161]
	v_readlane_b32 s4, v253, 48
	v_readlane_b32 s5, v253, 49
	v_lshlrev_b64 v[132:133], 4, v[0:1]
	v_add_u32_e32 v16, 0xa00, v0
	v_lshl_add_u64 v[2:3], v[128:129], 0, s[4:5]
	v_lshlrev_b64 v[2:3], 1, v[2:3]
	v_lshl_add_u64 v[10:11], v[4:5], 0, v[2:3]
	v_lshl_add_u64 v[2:3], v[6:7], 0, v[2:3]
	global_load_dwordx4 v[48:51], v[10:11], off
	global_load_dwordx4 v[52:55], v[2:3], off
	v_add_u32_e32 v2, 0x200, v0
	v_ashrrev_i32_e32 v10, 4, v2
	v_ashrrev_i32_e32 v11, 31, v10
	v_lshlrev_b64 v[130:131], 9, v[10:11]
	v_lshl_add_u64 v[12:13], v[130:131], 0, s[4:5]
	v_lshlrev_b64 v[12:13], 1, v[12:13]
	v_readlane_b32 s4, v253, 56
	v_ashrrev_i32_e32 v3, 31, v2
	v_lshl_add_u64 v[4:5], v[4:5], 0, v[12:13]
	v_lshl_add_u64 v[6:7], v[6:7], 0, v[12:13]
	v_readlane_b32 s5, v253, 57
	v_lshlrev_b64 v[134:135], 4, v[2:3]
	global_load_dwordx4 v[56:59], v[4:5], off
	global_load_dwordx4 v[60:63], v[6:7], off
	v_lshl_add_u64 v[4:5], s[4:5], 0, v[132:133]
	v_lshl_add_u64 v[6:7], s[4:5], 0, v[134:135]
	global_load_dwordx4 v[64:67], v[4:5], off
	global_load_dwordx4 v[68:71], v[6:7], off
	v_add_u32_e32 v6, 0x400, v0
	v_add_u32_e32 v4, 0x600, v0
	v_ashrrev_i32_e32 v7, 31, v6
	v_ashrrev_i32_e32 v5, 31, v4
	v_lshlrev_b64 v[136:137], 4, v[6:7]
	v_lshlrev_b64 v[138:139], 4, v[4:5]
	v_lshl_add_u64 v[12:13], s[4:5], 0, v[136:137]
	v_lshl_add_u64 v[14:15], s[4:5], 0, v[138:139]
	v_readlane_b32 s4, v253, 60
	v_readlane_b32 s5, v253, 61
	global_load_dwordx4 v[72:75], v[12:13], off
	global_load_dwordx4 v[76:79], v[14:15], off
	v_lshl_add_u64 v[12:13], s[4:5], 0, v[132:133]
	v_lshl_add_u64 v[14:15], s[4:5], 0, v[134:135]
	global_load_dwordx4 v[80:83], v[12:13], off
	global_load_dwordx4 v[84:87], v[14:15], off
	v_lshl_add_u64 v[12:13], s[4:5], 0, v[136:137]
	v_lshl_add_u64 v[14:15], s[4:5], 0, v[138:139]
	global_load_dwordx4 v[88:91], v[12:13], off
	global_load_dwordx4 v[92:95], v[14:15], off
	v_add_u32_e32 v12, 0x800, v0
	v_ashrrev_i32_e32 v13, 31, v12
	v_lshlrev_b64 v[140:141], 4, v[12:13]
	v_ashrrev_i32_e32 v17, 31, v16
	v_lshl_add_u64 v[14:15], s[4:5], 0, v[140:141]
	v_lshlrev_b64 v[142:143], 4, v[16:17]
	v_lshl_add_u64 v[18:19], s[4:5], 0, v[142:143]
	global_load_dwordx4 v[96:99], v[14:15], off
	global_load_dwordx4 v[100:103], v[18:19], off
	v_add_u32_e32 v14, 0xc00, v0
	v_ashrrev_i32_e32 v15, 31, v14
	v_add_u32_e32 v20, 0xe00, v0
	v_lshlrev_b64 v[144:145], 4, v[14:15]
	v_ashrrev_i32_e32 v21, 31, v20
	v_lshl_add_u64 v[18:19], s[4:5], 0, v[144:145]
	v_lshlrev_b64 v[146:147], 4, v[20:21]
	v_lshl_add_u64 v[22:23], s[4:5], 0, v[146:147]
	global_load_dwordx4 v[104:107], v[18:19], off
	global_load_dwordx4 v[108:111], v[22:23], off
	v_and_b32_e32 v22, 64, v193
	v_xor_b32_e32 v21, 32, v193
	v_add_u32_e32 v22, 64, v22
	v_cmp_lt_i32_e32 vcc, v21, v22
	v_and_b32_e32 v11, 15, v0
	v_lshlrev_b32_e32 v27, 2, v26
	v_cndmask_b32_e32 v21, v193, v21, vcc
	v_lshlrev_b32_e32 v206, 2, v21
	v_bitop3_b32 v21, v26, v0, 15 bitop3:0x78
	v_lshlrev_b32_e32 v208, 4, v21
	v_bitop3_b32 v21, v26, v11, 2 bitop3:0x36
	v_lshlrev_b32_e32 v209, 4, v21
	v_bitop3_b32 v21, v26, v11, 4 bitop3:0x36
	v_lshlrev_b32_e32 v210, 4, v21
	v_bitop3_b32 v21, v26, v11, 6 bitop3:0x36
	v_lshlrev_b32_e32 v211, 4, v21
	v_bitop3_b32 v21, v26, v11, 8 bitop3:0x36
	v_lshlrev_b32_e32 v212, 4, v21
	v_bitop3_b32 v21, v26, v11, 10 bitop3:0x36
	v_and_b32_e32 v25, 31, v0
	s_ashr_i32 s6, s8, 7
	v_lshl_or_b32 v13, s1, 5, v27
	v_lshlrev_b32_e32 v213, 4, v21
	v_bitop3_b32 v21, v26, v11, 12 bitop3:0x36
	v_bitop3_b32 v11, v26, v11, 14 bitop3:0x36
	v_readlane_b32 s13, v253, 21
	v_lshl_or_b32 v15, s6, 5, v25
	v_lshlrev_b32_e32 v215, 4, v11
	v_or_b32_e32 v11, 2, v13
	v_readlane_b32 s14, v253, 22
	v_readlane_b32 s15, v253, 23
	v_cmp_gt_i32_e64 s[12:13], v11, v15
	v_or_b32_e32 v11, 3, v13
	v_cmp_gt_i32_e64 s[14:15], v11, v15
	v_or_b32_e32 v11, 8, v13
	v_readlane_b32 s18, v253, 26
	v_readlane_b32 s19, v253, 27
	s_cmp_le_i32 s1, s6
	v_cmp_gt_i32_e64 s[16:17], v11, v15
	v_or_b32_e32 v11, 9, v13
	v_readlane_b32 s20, v253, 28
	v_readlane_b32 s21, v253, 29
	s_cselect_b64 s[4:5], -1, 0
	s_lshl_b32 s7, s1, 13
	v_cmp_gt_i32_e64 s[18:19], v11, v15
	v_or_b32_e32 v11, 10, v13
	v_readlane_b32 s22, v253, 30
	v_readlane_b32 s23, v253, 31
	v_lshlrev_b32_e32 v9, 8, v25
	s_add_i32 s7, s7, 0
	v_cmp_gt_i32_e64 s[20:21], v11, v15
	v_or_b32_e32 v11, 11, v13
	v_readlane_b32 s24, v253, 32
	v_readlane_b32 s25, v253, 33
	v_add_u32_e32 v202, s7, v9
	s_lshl_b32 s7, s6, 13
	s_movk_i32 s2, 0x90
	s_add_i32 s6, 0, 0x20000
; #define MFMA32(a, b, c) __builtin_amdgcn_mfma_f32_32x32x16_bf16((a), (b), (c), 0, 0, 0)
; DI unsigned pk2(float lo, float hi) { return pg8::cvt_pk_bf16(lo, hi); }
; template <int DV> DI void la3(const Ctx& c, const bf16* __restrict__ QT, const bf16* __restrict__ KT, const bf16* __restrict__ VT, const bf16* __restrict__ ST, const float* __restrict__ gain, const bf16* __restrict__ gate, int gate_ld, bf16* __restrict__ OUT, int out_col0) {
;     constexpr int NP = (DV / 32) * 2 / 8, NEB = DV / 32;
;     const int l31 = c.lane & 31, hi = c.lane >> 5;
;     unsigned char* QL = c.lds; unsigned char* KL = c.lds + 16384; unsigned char* VL = c.lds + 32768; unsigned char* SL = c.lds + 65536;
;     bf16* Al = (bf16*)(c.lds + 131072);
;     float* SS = (float*)(c.lds + 131072 + 9216);
;     const int eb = (c.wave * NP) >> 1;
;     const int ib1 = c.wave >> 1, jb1 = c.wave & 1;
;     f32x4 gn[4];
; #pragma unroll
;     for (int g = 0; g < 4; ++g) gn[g] = *(const f32x4*)(gain + 32 * eb + 8 * g + 4 * hi);
;     ...
;     La3Stage<DV> stg;
;     if (c.bid < 2048) la3_issue<DV>(stg, QT, KT, VT, ST, c.bid, c.tid);
;     for (int u = c.bid; u < 2048; u += c.G) {
;         const int cp = u >> 2, h = u & 3; const size_t row0 = (size_t)cp * 64;
;         la3_commit<DV>(stg, c.lds, c.tid);
;         __syncthreads();
;         if (c.wave < 4) {
;             f32x16 acc; for (int r = 0; r < 16; ++r) acc[r] = 0.f;
;             if (jb1 <= ib1) {
; #pragma unroll
;                 for (int kk = 0; kk < 8; ++kk) acc = MFMA32(LA3_F256(KL, 32 * jb1 + l31, kk), LA3_F256(QL, 32 * ib1 + l31, kk), acc);
;             }
; #pragma unroll
;             for (int g = 0; g < 4; ++g) { float v[4];
; #pragma unroll
;                 for (int x = 0; x < 4; ++x) { const int j = 32 * jb1 + 8 * g + 4 * hi + x, i = 32 * ib1 + l31; v[x] = (j <= i) ? acc[4 * g + x] : 0.f; }
;                 u32x2 w; w.x = pk2(v[0], v[1]); w.y = pk2(v[2], v[3]);
;                 *(u32x2*)(Al + (32 * ib1 + l31) * 72 + 32 * jb1 + 8 * g + 4 * hi) = w; }
	s_lshl_b32 s1, s1, 6
	v_cmp_gt_i32_e64 s[22:23], v11, v15
	v_or_b32_e32 v11, 16, v13
	v_readlane_b32 s26, v253, 34
	v_readlane_b32 s27, v253, 35
	v_mul_lo_u32 v17, v15, s2
	s_add_i32 s1, s1, s6
	v_lshlrev_b32_e32 v18, 3, v26
	v_cmp_gt_i32_e64 s[24:25], v11, v15
	v_or_b32_e32 v11, 17, v13
	v_add3_u32 v204, s1, v17, v18
	s_lshl_b32 s1, s0, 12
	v_cmp_gt_i32_e64 s[26:27], v11, v15
	v_or_b32_e32 v11, 18, v13
	s_add_i32 s1, s1, 0
	v_cmp_gt_i32_e64 s[28:29], v11, v15
	v_or_b32_e32 v11, 19, v13
	v_add_u32_e32 v17, s6, v28
	v_lshl_add_u32 v18, v25, 7, s1
	s_lshl_b32 s6, s0, 13
	s_add_i32 s1, 0, 0x10000
	s_and_b32 s42, s8, 0x3fffffc0
	v_cmp_gt_i32_e64 s[30:31], v11, v15
	v_or_b32_e32 v11, 24, v13
	v_lshrrev_b32_e32 v1, 27, v1
	s_add_i32 s7, s7, 0
	s_add_i32 s6, s1, s6
	v_cmp_gt_i32_e64 s[34:35], v11, v15
	v_or_b32_e32 v11, 25, v13
	s_lshl_b32 s42, s42, 2
	v_readlane_b32 s2, v254, 44
	v_add_u32_e32 v1, v0, v1
	v_and_b32_e32 v24, 63, v0
	v_add_u32_e32 v203, s7, v9
	v_add_u32_e32 v205, s6, v9
	v_cmp_gt_i32_e64 s[36:37], v11, v15
	v_or_b32_e32 v11, 26, v13
	v_add_u32_e32 v216, 0, v9
	s_add_i32 s42, s2, s42
	v_or_b32_e32 v9, 32, v25
	v_ashrrev_i32_e32 v27, 3, v0
	v_ashrrev_i32_e32 v29, 3, v2
	v_ashrrev_i32_e32 v31, 3, v6
	v_ashrrev_i32_e32 v113, 3, v4
	v_ashrrev_i32_e32 v115, 4, v6
	v_ashrrev_i32_e32 v118, 4, v4
	v_ashrrev_i32_e32 v12, 4, v12
	v_ashrrev_i32_e32 v16, 4, v16
	v_ashrrev_i32_e32 v14, 4, v14
	v_ashrrev_i32_e32 v20, 4, v20
	v_ashrrev_i32_e32 v148, 5, v1
	v_and_b32_e32 v1, 0xffffffe0, v1
	v_and_b32_e32 v19, 7, v0
	v_cmp_gt_u32_e64 s[6:7], 32, v24
	v_lshl_or_b32 v207, s0, 7, v28
	v_cmp_gt_i32_e64 s[8:9], v13, v15
	v_cmp_lt_i32_e64 s[10:11], v13, v15
	v_cmp_gt_i32_e64 s[38:39], v11, v15
	v_or_b32_e32 v11, 27, v13
	v_bitop3_b32 v13, v26, v0, 7 bitop3:0x78
	v_lshl_add_u32 v217, v24, 2, s42
	v_mul_u32_u24_e32 v22, 0x90, v9
	v_lshl_add_u32 v219, v9, 2, s2
	v_lshlrev_b32_e32 v9, 8, v8
	v_xor_b32_e32 v8, v8, v0
	v_lshlrev_b32_e32 v24, 8, v10
	v_xor_b32_e32 v10, v10, v0
	v_lshl_add_u32 v28, v27, 7, 0
	v_xor_b32_e32 v27, v27, v0
	v_lshl_add_u32 v30, v29, 7, 0
	v_xor_b32_e32 v29, v29, v0
	v_lshl_add_u32 v112, v31, 7, 0
	v_xor_b32_e32 v31, v31, v0
	v_lshl_add_u32 v114, v113, 7, 0
	v_xor_b32_e32 v113, v113, v0
	v_lshl_add_u32 v117, v115, 8, s1
	v_xor_b32_e32 v115, v115, v0
	v_lshl_add_u32 v119, v118, 8, s1
	v_xor_b32_e32 v118, v118, v0
	v_lshl_add_u32 v120, v12, 8, s1
	v_xor_b32_e32 v12, v12, v0
	v_lshl_add_u32 v121, v16, 8, s1
	v_xor_b32_e32 v16, v16, v0
	v_lshl_add_u32 v122, v14, 8, s1
	v_xor_b32_e32 v14, v14, v0
	v_lshl_add_u32 v123, v20, 8, s1
	v_xor_b32_e32 v20, v20, v0
	v_sub_u32_e32 v0, v0, v1
	v_lshrrev_b32_e32 v1, 27, v3
	v_add_u32_e32 v1, v2, v1
	v_ashrrev_i32_e32 v152, 5, v1
	v_and_b32_e32 v1, 0xffffffe0, v1
	v_sub_u32_e32 v1, v2, v1
	v_lshrrev_b32_e32 v2, 27, v7
	v_lshrrev_b32_e32 v3, 27, v5
	v_add_u32_e32 v2, v6, v2
	v_add_u32_e32 v3, v4, v3
	v_lshlrev_b32_e32 v8, 4, v8
	v_lshlrev_b32_e32 v10, 4, v10
	v_mov_b32_e32 v116, s1
	s_cmp_lt_i32 s0, 4
	v_ashrrev_i32_e32 v156, 5, v2
	v_and_b32_e32 v2, 0xffffffe0, v2
	v_ashrrev_i32_e32 v170, 5, v3
	v_and_b32_e32 v3, 0xffffffe0, v3
	s_movk_i32 s0, 0x410
	v_lshlrev_b32_e32 v214, 4, v21
	v_cmp_gt_i32_e64 s[40:41], v11, v15
	v_mul_u32_u24_e32 v11, 0x90, v25
	v_bitop3_b32 v15, v26, v19, 2 bitop3:0x36
	v_bitop3_b32 v21, v26, v19, 4 bitop3:0x36
	v_bitop3_b32 v19, v26, v19, 6 bitop3:0x36
	v_lshl_add_u32 v218, v25, 2, s2
	v_and_b32_e32 v8, 0xf0, v8
	v_and_b32_e32 v10, 0xf0, v10
	v_lshlrev_b32_e32 v27, 4, v27
	v_lshlrev_b32_e32 v29, 4, v29
	v_lshlrev_b32_e32 v31, 4, v31
	v_lshlrev_b32_e32 v113, 4, v113
	v_lshlrev_b32_e32 v115, 4, v115
	v_lshlrev_b32_e32 v118, 4, v118
	v_lshlrev_b32_e32 v12, 4, v12
	v_lshlrev_b32_e32 v16, 4, v16
	v_lshlrev_b32_e32 v14, 4, v14
	v_lshlrev_b32_e32 v20, 4, v20
	v_sub_u32_e32 v2, v6, v2
	v_sub_u32_e32 v3, v4, v3
	v_lshl_add_u64 v[174:175], s[60:61], 0, v[160:161]
	v_lshl_add_u64 v[176:177], s[94:95], 0, v[160:161]
	v_mad_u32_u24 v160, v25, s0, v116
	v_mul_lo_u32 v5, v148, s0
	v_mul_lo_u32 v6, v152, s0
	v_mul_lo_u32 v7, v156, s0
	v_mul_lo_u32 v25, v170, s0
	v_lshlrev_b32_e32 v13, 4, v13
	v_lshlrev_b32_e32 v15, 4, v15
	v_lshlrev_b32_e32 v21, 4, v21
	v_lshlrev_b32_e32 v19, 4, v19
	v_or_b32_e32 v23, v8, v9
	v_or_b32_e32 v26, v10, v24
	v_and_b32_e32 v27, 0x70, v27
	v_and_b32_e32 v29, 0x70, v29
	v_and_b32_e32 v31, 0x70, v31
	v_and_b32_e32 v113, 0x70, v113
	v_add_u32_e32 v9, s1, v9
	v_add_u32_e32 v24, s1, v24
	v_and_b32_e32 v115, 0xf0, v115
	v_and_b32_e32 v118, 0xf0, v118
	v_and_b32_e32 v12, 0xf0, v12
	v_and_b32_e32 v16, 0xf0, v16
	v_and_b32_e32 v14, 0xf0, v14
	v_and_b32_e32 v20, 0xf0, v20
	v_lshlrev_b32_e32 v150, 3, v0
	v_lshlrev_b32_e32 v154, 3, v1
	v_lshlrev_b32_e32 v158, 3, v2
	v_lshlrev_b32_e32 v172, 3, v3
	v_add_u32_e32 v4, 0x8200, v160
	v_add_u32_e32 v5, s1, v5
	v_lshlrev_b32_e32 v0, 5, v0
	v_add_u32_e32 v6, s1, v6
	v_lshlrev_b32_e32 v1, 5, v1
	v_add_u32_e32 v7, s1, v7
	v_lshlrev_b32_e32 v2, 5, v2
	v_add_u32_e32 v25, s1, v25
	v_lshlrev_b32_e32 v3, 5, v3
	s_cselect_b64 s[74:75], -1, 0
	v_ashrrev_i32_e32 v149, 31, v148
	v_ashrrev_i32_e32 v151, 31, v150
	v_ashrrev_i32_e32 v153, 31, v152
	v_ashrrev_i32_e32 v155, 31, v154
	v_ashrrev_i32_e32 v157, 31, v156
	v_ashrrev_i32_e32 v159, 31, v158
	v_ashrrev_i32_e32 v171, 31, v170
	v_ashrrev_i32_e32 v173, 31, v172
	s_lshl_b32 s67, s66, 8
	v_add_u32_e32 v220, 0, v23
	v_add_u32_e32 v221, 0, v26
	v_add_u32_e32 v222, v28, v27
	v_add_u32_e32 v223, v30, v29
	v_add_u32_e32 v224, v112, v31
	v_add_u32_e32 v225, v114, v113
	v_add_u32_e32 v226, v9, v8
	v_add_u32_e32 v227, v24, v10
	v_add_u32_e32 v228, v117, v115
	v_add_u32_e32 v229, v119, v118
	v_add_u32_e32 v230, v120, v12
	v_add_u32_e32 v231, v121, v16
	v_add_u32_e32 v232, v122, v14
	v_add_u32_e32 v233, v123, v20
	v_add_u32_e32 v234, v17, v11
	v_add_u32_e32 v235, v17, v22
	v_add_u32_e32 v236, v4, v207
	v_add_u32_e32 v237, v5, v0
	v_add_u32_e32 v238, v6, v1
	v_add_u32_e32 v239, v7, v2
	v_add_u32_e32 v240, v25, v3
	v_add_u32_e32 v241, v18, v13
	v_add_u32_e32 v242, v18, v15
	v_add_u32_e32 v243, v18, v21
	v_add_u32_e32 v244, v18, v19
	v_readlane_b32 s80, v253, 51
	s_mov_b32 s86, s90
	s_branch .LBB0_330

; __device__ __forceinline__ unsigned xb_ld(unsigned* p)              { return __hip_atomic_load(p, __ATOMIC_RELAXED, __HIP_MEMORY_SCOPE_AGENT); }
; __device__ __forceinline__ unsigned xb_add(unsigned* p, unsigned v) { return __hip_atomic_fetch_add(p, v, __ATOMIC_RELAXED, __HIP_MEMORY_SCOPE_AGENT); }
; #define XB_SPIN(cond, bar) do { unsigned _sp = 0; while (cond) { __builtin_amdgcn_s_sleep(1); \
;     if ((++_sp & 255u) == 0u) { if (xb_ld(&(bar)[XB_TMO])) break; if (_sp > XB_SPIN_CAP) { atomicAdd(&(bar)[XB_TMO], 1u); break; } } } } while (0)
; __device__ __forceinline__ void xcd_barrier(const XcdBarrier& b) {
;     asm volatile("s_waitcnt vmcnt(0)" ::: "memory");
;     __syncthreads();
;     if (threadIdx.x == 0) {
;         unsigned* bar = b.bar;
;         __builtin_amdgcn_s_waitcnt(0);
;         unsigned nloc = b.st[0], nx = b.st[1];
;         if (nloc == 0u) { xcd_barrier_complete(bar, b.x, nloc, nx); b.st[0] = nloc; b.st[1] = nx; }
;         const unsigned old = xb_add(&bar[XB_XSUB(b.x)], 1u);
;         const unsigned gen = old / nloc;
;         if (old + 1u == (gen + 1u) * nloc) {
;             __builtin_amdgcn_fence(__ATOMIC_RELEASE, "agent");
;             asm volatile("s_waitcnt vmcnt(0)" ::: "memory");
;             const unsigned og = xb_add(&bar[XB_TOP], 1u);
;             const unsigned tg = og / nx;
;             if (og + 1u == (tg + 1u) * nx) xb_add(&bar[XB_TOPGEN], 1u);
;             else XB_SPIN(xb_ld(&bar[XB_TOPGEN]) == tg, bar);
;             __builtin_amdgcn_fence(__ATOMIC_ACQUIRE, "agent");
;             xb_add(&bar[XB_XGEN(b.x)], 1u);
;             asm volatile("s_waitcnt vmcnt(0)" ::: "memory");
;         } else {
;             XB_SPIN(xb_ld(&bar[XB_XGEN(b.x)]) == gen, bar);
;             __builtin_amdgcn_fence(__ATOMIC_ACQUIRE, "agent");
;             asm volatile("s_waitcnt vmcnt(0)" ::: "memory");
;         }
;     }
;     __syncthreads();
; }
.LBB0_339:
	s_getreg_b32 s4, hwreg(HW_REG_XCC_ID, 0, 4)
	s_waitcnt vmcnt(0)
	s_barrier
	s_and_saveexec_b64 s[0:1], s[68:69]
	v_readlane_b32 s24, v254, 63
	s_xor_b64 s[0:1], exec, s[0:1]
	v_readlane_b32 s25, v255, 0
	s_cbranch_execz .LBB0_392
	v_readlane_b32 s2, v254, 42
	s_waitcnt vmcnt(0) expcnt(0) lgkmcnt(0)
	buffer_inv sc1
	s_and_b32 s10, s4, 15
	s_lshl_b32 s5, s10, 8
	v_mov_b32_e32 v0, s2
	ds_read_b32 v2, v0
	v_readlane_b32 s2, v254, 43
	s_add_u32 s12, s46, s5
	s_addc_u32 s13, s47, 0
	v_mov_b32_e32 v3, 1
	v_mov_b32_e32 v0, s2
	ds_read_b32 v6, v0
	v_mov_b32_e32 v5, 0x1400
	s_waitcnt lgkmcnt(0)
	global_atomic_add v3, v5, v3, s[12:13] sc0
	v_cvt_f32_u32_e32 v4, v2
	s_waitcnt vmcnt(0)
	v_mov_b32_e32 v5, v3
	v_sub_u32_e32 v3, 0, v2
	v_rcp_iflag_f32_e32 v4, v4
	s_nop 0
	v_mul_f32_e32 v4, 0x4f7ffffe, v4
	v_cvt_u32_f32_e32 v4, v4
	v_mul_lo_u32 v1, v3, v4
	v_mul_hi_u32 v1, v4, v1
	v_add_u32_e32 v1, v4, v1
	v_mul_hi_u32 v1, v5, v1
	v_mul_lo_u32 v3, v1, v2
	v_sub_u32_e32 v3, v5, v3
	v_add_u32_e32 v4, 1, v1
	v_cmp_ge_u32_e32 vcc, v3, v2
	s_nop 1
	v_cndmask_b32_e32 v1, v1, v4, vcc
	v_sub_u32_e32 v4, v3, v2
	v_cndmask_b32_e32 v3, v3, v4, vcc
	v_add_u32_e32 v4, 1, v1
	v_cmp_ge_u32_e32 vcc, v3, v2
	v_add_u32_e32 v3, 1, v5
	s_nop 0
	v_cndmask_b32_e32 v1, v1, v4, vcc
	v_mul_lo_u32 v4, v2, v1
	v_add_u32_e32 v2, v4, v2
	v_mul_lo_u32 v7, v1, v6
	v_cmp_ne_u32_e32 vcc, v3, v2
	s_mov_b32 s8, 0
	s_cbranch_vccnz .Lnb_loop_4
	buffer_wbl2 sc1
	v_mov_b32_e32 v8, 1
	v_mov_b32_e32 v9, 0x2404
	s_waitcnt vmcnt(0)
	global_atomic_add v9, v8, s[46:47]
	v_add_u32_e32 v9, 0x100, v9
	global_atomic_add v9, v8, s[46:47]
	v_add_u32_e32 v9, 0x100, v9
	global_atomic_add v9, v8, s[46:47]
	v_add_u32_e32 v9, 0x100, v9
	global_atomic_add v9, v8, s[46:47]
	v_add_u32_e32 v9, 0x100, v9
	global_atomic_add v9, v8, s[46:47]
	v_add_u32_e32 v9, 0x100, v9
	global_atomic_add v9, v8, s[46:47]
	v_add_u32_e32 v9, 0x100, v9
	global_atomic_add v9, v8, s[46:47]
	v_add_u32_e32 v9, 0x100, v9
	global_atomic_add v9, v8, s[46:47]
	v_add_u32_e32 v9, 0x100, v9
	global_atomic_add v9, v8, s[46:47]
	v_add_u32_e32 v9, 0x100, v9
	global_atomic_add v9, v8, s[46:47]
	v_add_u32_e32 v9, 0x100, v9
	global_atomic_add v9, v8, s[46:47]
	v_add_u32_e32 v9, 0x100, v9
	global_atomic_add v9, v8, s[46:47]
	v_add_u32_e32 v9, 0x100, v9
	global_atomic_add v9, v8, s[46:47]
	v_add_u32_e32 v9, 0x100, v9
	global_atomic_add v9, v8, s[46:47]
	v_add_u32_e32 v9, 0x100, v9
	global_atomic_add v9, v8, s[46:47]
	v_add_u32_e32 v9, 0x100, v9
	global_atomic_add v9, v8, s[46:47]

; __device__ __forceinline__ unsigned xb_ld(unsigned* p)              { return __hip_atomic_load(p, __ATOMIC_RELAXED, __HIP_MEMORY_SCOPE_AGENT); }
; __device__ __forceinline__ unsigned xb_add(unsigned* p, unsigned v) { return __hip_atomic_fetch_add(p, v, __ATOMIC_RELAXED, __HIP_MEMORY_SCOPE_AGENT); }
; #define XB_SPIN(cond, bar) do { unsigned _sp = 0; while (cond) { __builtin_amdgcn_s_sleep(1); \
;     if ((++_sp & 255u) == 0u) { if (xb_ld(&(bar)[XB_TMO])) break; if (_sp > XB_SPIN_CAP) { atomicAdd(&(bar)[XB_TMO], 1u); break; } } } } while (0)
; __device__ __forceinline__ void xcd_barrier(const XcdBarrier& b) {
;     ...
;         const unsigned old = xb_add(&bar[XB_XSUB(b.x)], 1u);
;         const unsigned gen = old / nloc;
;         if (old + 1u == (gen + 1u) * nloc) {
;             __builtin_amdgcn_fence(__ATOMIC_RELEASE, "agent");
;             asm volatile("s_waitcnt vmcnt(0)" ::: "memory");
;             const unsigned og = xb_add(&bar[XB_TOP], 1u);
;             const unsigned tg = og / nx;
;             if (og + 1u == (tg + 1u) * nx) xb_add(&bar[XB_TOPGEN], 1u);
;             else XB_SPIN(xb_ld(&bar[XB_TOPGEN]) == tg, bar);
;             __builtin_amdgcn_fence(__ATOMIC_ACQUIRE, "agent");
;             xb_add(&bar[XB_XGEN(b.x)], 1u);
;             asm volatile("s_waitcnt vmcnt(0)" ::: "memory");
;         } else {
;             XB_SPIN(xb_ld(&bar[XB_XGEN(b.x)]) == gen, bar);
;             __builtin_amdgcn_fence(__ATOMIC_ACQUIRE, "agent");
;             asm volatile("s_waitcnt vmcnt(0)" ::: "memory");
;         }
;     }
;     __syncthreads();
; }
.Lnb_done_4:
	s_waitcnt vmcnt(0)
.LBB0_392:
	s_or_b64 exec, exec, s[0:1]
	v_readlane_b32 s8, v253, 0
	v_readlane_b32 s10, v253, 2
	v_readlane_b32 s11, v253, 3
	s_mov_b64 s[6:7], 0
	s_mov_b64 s[0:1], s[10:11]
	s_mov_b64 s[66:67], 0x1000
	s_waitcnt lgkmcnt(0)
	s_barrier
	v_readlane_b32 s9, v253, 1

; __device__ __forceinline__ unsigned xb_ld(unsigned* p)              { return __hip_atomic_load(p, __ATOMIC_RELAXED, __HIP_MEMORY_SCOPE_AGENT); }
; __device__ __forceinline__ unsigned xb_add(unsigned* p, unsigned v) { return __hip_atomic_fetch_add(p, v, __ATOMIC_RELAXED, __HIP_MEMORY_SCOPE_AGENT); }
; #define XB_SPIN(cond, bar) do { unsigned _sp = 0; while (cond) { __builtin_amdgcn_s_sleep(1); \
;     if ((++_sp & 255u) == 0u) { if (xb_ld(&(bar)[XB_TMO])) break; if (_sp > XB_SPIN_CAP) { atomicAdd(&(bar)[XB_TMO], 1u); break; } } } } while (0)
; __device__ __forceinline__ void xcd_barrier(const XcdBarrier& b) {
;     asm volatile("s_waitcnt vmcnt(0)" ::: "memory");
;     __syncthreads();
;     if (threadIdx.x == 0) {
;         unsigned* bar = b.bar;
;         __builtin_amdgcn_s_waitcnt(0);
;         unsigned nloc = b.st[0], nx = b.st[1];
;         if (nloc == 0u) { xcd_barrier_complete(bar, b.x, nloc, nx); b.st[0] = nloc; b.st[1] = nx; }
;         const unsigned old = xb_add(&bar[XB_XSUB(b.x)], 1u);
;         const unsigned gen = old / nloc;
;         if (old + 1u == (gen + 1u) * nloc) {
;             __builtin_amdgcn_fence(__ATOMIC_RELEASE, "agent");
;             asm volatile("s_waitcnt vmcnt(0)" ::: "memory");
;             const unsigned og = xb_add(&bar[XB_TOP], 1u);
;             const unsigned tg = og / nx;
;             if (og + 1u == (tg + 1u) * nx) xb_add(&bar[XB_TOPGEN], 1u);
;             else XB_SPIN(xb_ld(&bar[XB_TOPGEN]) == tg, bar);
;             __builtin_amdgcn_fence(__ATOMIC_ACQUIRE, "agent");
;             xb_add(&bar[XB_XGEN(b.x)], 1u);
;             asm volatile("s_waitcnt vmcnt(0)" ::: "memory");
;         } else {
;             XB_SPIN(xb_ld(&bar[XB_XGEN(b.x)]) == gen, bar);
;             __builtin_amdgcn_fence(__ATOMIC_ACQUIRE, "agent");
;             asm volatile("s_waitcnt vmcnt(0)" ::: "memory");
;         }
;     }
;     __syncthreads();
; }
.LBB0_469:
	s_getreg_b32 s4, hwreg(HW_REG_XCC_ID, 0, 4)
	s_waitcnt vmcnt(0)
	s_waitcnt lgkmcnt(0)
	s_barrier
	s_and_saveexec_b64 s[0:1], s[68:69]
	s_cbranch_execz .LBB0_521
	v_readlane_b32 s2, v254, 42
	s_waitcnt vmcnt(0) expcnt(0) lgkmcnt(0)
	buffer_inv sc1
	s_and_b32 s10, s4, 15
	s_lshl_b32 s5, s10, 8
	v_mov_b32_e32 v0, s2
	ds_read_b32 v2, v0
	v_readlane_b32 s2, v254, 43
	s_add_u32 s12, s46, s5
	s_addc_u32 s13, s47, 0
	v_mov_b32_e32 v3, 1
	v_mov_b32_e32 v0, s2
	ds_read_b32 v6, v0
	v_mov_b32_e32 v5, 0x1400
	s_waitcnt lgkmcnt(0)
	global_atomic_add v3, v5, v3, s[12:13] sc0
	v_cvt_f32_u32_e32 v4, v2
	s_waitcnt vmcnt(0)
	v_mov_b32_e32 v5, v3
	v_sub_u32_e32 v3, 0, v2
	v_rcp_iflag_f32_e32 v4, v4
	s_nop 0
	v_mul_f32_e32 v4, 0x4f7ffffe, v4
	v_cvt_u32_f32_e32 v4, v4
	v_mul_lo_u32 v1, v3, v4
	v_mul_hi_u32 v1, v4, v1
	v_add_u32_e32 v1, v4, v1
	v_mul_hi_u32 v1, v5, v1
	v_mul_lo_u32 v3, v1, v2
	v_sub_u32_e32 v3, v5, v3
	v_add_u32_e32 v4, 1, v1
	v_cmp_ge_u32_e32 vcc, v3, v2
	s_nop 1
	v_cndmask_b32_e32 v1, v1, v4, vcc
	v_sub_u32_e32 v4, v3, v2
	v_cndmask_b32_e32 v3, v3, v4, vcc
	v_add_u32_e32 v4, 1, v1
	v_cmp_ge_u32_e32 vcc, v3, v2
	v_add_u32_e32 v3, 1, v5
	s_nop 0
	v_cndmask_b32_e32 v1, v1, v4, vcc
	v_mul_lo_u32 v4, v2, v1
	v_add_u32_e32 v2, v4, v2
	v_mul_lo_u32 v7, v1, v6
	v_cmp_ne_u32_e32 vcc, v3, v2
	s_mov_b32 s8, 0
	s_cbranch_vccnz .Lnb_loop_5
	buffer_wbl2 sc1
	v_mov_b32_e32 v8, 1
	v_mov_b32_e32 v9, 0x2404
	s_waitcnt vmcnt(0)
	global_atomic_add v9, v8, s[46:47]
	v_add_u32_e32 v9, 0x100, v9
	global_atomic_add v9, v8, s[46:47]
	v_add_u32_e32 v9, 0x100, v9
	global_atomic_add v9, v8, s[46:47]
	v_add_u32_e32 v9, 0x100, v9
	global_atomic_add v9, v8, s[46:47]
	v_add_u32_e32 v9, 0x100, v9
	global_atomic_add v9, v8, s[46:47]
	v_add_u32_e32 v9, 0x100, v9
	global_atomic_add v9, v8, s[46:47]
	v_add_u32_e32 v9, 0x100, v9
	global_atomic_add v9, v8, s[46:47]
	v_add_u32_e32 v9, 0x100, v9
	global_atomic_add v9, v8, s[46:47]
	v_add_u32_e32 v9, 0x100, v9
	global_atomic_add v9, v8, s[46:47]
	v_add_u32_e32 v9, 0x100, v9
	global_atomic_add v9, v8, s[46:47]
	v_add_u32_e32 v9, 0x100, v9
	global_atomic_add v9, v8, s[46:47]
	v_add_u32_e32 v9, 0x100, v9
	global_atomic_add v9, v8, s[46:47]
	v_add_u32_e32 v9, 0x100, v9
	global_atomic_add v9, v8, s[46:47]
	v_add_u32_e32 v9, 0x100, v9
	global_atomic_add v9, v8, s[46:47]
	v_add_u32_e32 v9, 0x100, v9
	global_atomic_add v9, v8, s[46:47]
	v_add_u32_e32 v9, 0x100, v9
	global_atomic_add v9, v8, s[46:47]

; DI void sb_attention(const Ctx& c, const bf16* Qn, const bf16* Kn, const bf16* Vv, bf16* OUT) {
;     const int l31 = c.lane & 31, hi = c.lane >> 5;
;     bf16* vl = (bf16*)(c.lds + 32768 + c.wave * 8192);
;     for (int u = c.gw; u < 8192; u += c.NGW) {
;         const int qb = u & 511, h = (u >> 9) & 7, b = u >> 12;
;         const size_t row0 = (size_t)b * SEQ + 32 * qb;
;         bf16x8 qf[4];
; #pragma unroll
;         for (int kk = 0; kk < 4; ++kk) qf[kk] = *(const bf16x8*)(Qn + (row0 + l31) * 512 + 64 * h + 16 * kk + 8 * hi);
;         float R2 = 0.f;
;         f32x16 O0, O1; for (int r = 0; r < 16; ++r) { O0[r] = 0.f; O1[r] = 0.f; }
;         bf16x8 kfn[4]; u32x4 vn[4];
;         { const size_t krow0 = (size_t)b * SEQ + 32 * qb;
; #pragma unroll
;           for (int i = 0; i < 4; ++i) { const int idx = c.lane + 64 * i, key = idx >> 3, c8 = idx & 7; vn[i] = *(const u32x4*)(Vv + (krow0 + key) * 512 + 64 * h + 8 * c8); }
; #pragma unroll
;           for (int kk = 0; kk < 4; ++kk) kfn[kk] = *(const bf16x8*)(Kn + (krow0 + l31) * 512 + 64 * h + 16 * kk + 8 * hi); }
;     ...
;             bf16x8 kf[4]; u32x4 vv[4];
; #pragma unroll
;             for (int i = 0; i < 4; ++i) { kf[i] = kfn[i]; vv[i] = vn[i]; }
;             if (kt > 0) {
;                 const size_t krow1 = (size_t)b * SEQ + 32 * (kt - 1);
; #pragma unroll
; __device__ __forceinline__ void xcd_barrier(const XcdBarrier& b) {
;     ...
;         const unsigned old = xb_add(&bar[XB_XSUB(b.x)], 1u);
;         const unsigned gen = old / nloc;
;         if (old + 1u == (gen + 1u) * nloc) {
;             __builtin_amdgcn_fence(__ATOMIC_RELEASE, "agent");
;             asm volatile("s_waitcnt vmcnt(0)" ::: "memory");
;             const unsigned og = xb_add(&bar[XB_TOP], 1u);
;             const unsigned tg = og / nx;
;             if (og + 1u == (tg + 1u) * nx) xb_add(&bar[XB_TOPGEN], 1u);
;             else XB_SPIN(xb_ld(&bar[XB_TOPGEN]) == tg, bar);
;             __builtin_amdgcn_fence(__ATOMIC_ACQUIRE, "agent");
;             xb_add(&bar[XB_XGEN(b.x)], 1u);
;             asm volatile("s_waitcnt vmcnt(0)" ::: "memory");
;         } else {
;             XB_SPIN(xb_ld(&bar[XB_XGEN(b.x)]) == gen, bar);
;             __builtin_amdgcn_fence(__ATOMIC_ACQUIRE, "agent");
;             asm volatile("s_waitcnt vmcnt(0)" ::: "memory");
;         }
;     }
;     __syncthreads();
; }
.Lnb_done_5:
	s_waitcnt vmcnt(0)
.LBB0_521:
	s_or_b64 exec, exec, s[0:1]
	s_waitcnt lgkmcnt(0)
	v_mov_b32_e32 v0, v186
	s_barrier
	s_nop 0
	v_readfirstlane_b32 s0, v0
	s_ashr_i32 s1, s0, 6
	s_add_i32 s40, s1, s72
	s_cmpk_lt_i32 s40, 0x2000
	s_cbranch_scc0 .LBB0_532
	v_and_b32_e32 v6, 64, v193
	v_xor_b32_e32 v5, 32, v193
	v_add_u32_e32 v6, 64, v6
	v_bfe_u32 v3, v0, 5, 1
	v_cmp_lt_i32_e32 vcc, v5, v6
	v_lshlrev_b32_e32 v4, 2, v3
	v_and_b32_e32 v112, 31, v0
	v_cndmask_b32_e32 v5, v193, v5, vcc
	v_lshlrev_b32_e32 v113, 2, v5
	v_or_b32_e32 v5, 2, v4
	v_cmp_lt_u32_e64 s[10:11], v5, v112
	v_or_b32_e32 v5, 3, v4
	v_cmp_lt_u32_e64 s[12:13], v5, v112
	v_or_b32_e32 v5, 8, v4
	v_cmp_lt_u32_e64 s[14:15], v5, v112
	v_or_b32_e32 v5, 9, v4
	v_cmp_lt_u32_e64 s[16:17], v5, v112
	v_or_b32_e32 v5, 10, v4
	v_cmp_lt_u32_e64 s[18:19], v5, v112
	v_or_b32_e32 v5, 11, v4
	v_cmp_lt_u32_e64 s[20:21], v5, v112
	v_or_b32_e32 v5, 16, v4
	v_cmp_lt_u32_e64 s[22:23], v5, v112
	v_or_b32_e32 v5, 17, v4
	v_cmp_lt_u32_e64 s[24:25], v5, v112
	v_or_b32_e32 v5, 18, v4
	v_cmp_lt_u32_e64 s[26:27], v5, v112
	v_or_b32_e32 v5, 19, v4
	v_cmp_lt_u32_e64 s[28:29], v5, v112
	v_or_b32_e32 v5, 24, v4
	v_and_b32_e32 v1, 63, v0
	v_cmp_lt_u32_e64 s[30:31], v5, v112
	v_or_b32_e32 v5, 25, v4
	v_cmp_gt_u32_e64 s[4:5], 32, v1
	v_or_b32_e32 v1, 1, v4
	v_cmp_lt_u32_e64 s[34:35], v5, v112
	v_or_b32_e32 v5, 26, v4
	s_lshl_b32 s1, s1, 13
	v_cmp_lt_u32_e64 s[8:9], v1, v112
	v_cmp_lt_u32_e64 s[36:37], v5, v112
	v_or_b32_e32 v5, 27, v4
	v_mul_u32_u24_e32 v1, 0x48, v1
	s_add_i32 s1, s1, 0
	v_cmp_lt_u32_e64 s[38:39], v5, v112
	v_lshlrev_b32_e32 v5, 1, v112
	v_lshlrev_b32_e32 v1, 1, v1
	v_lshlrev_b32_e32 v160, 4, v3
	v_add3_u32 v121, s1, v1, v5
	v_lshlrev_b32_e32 v1, 4, v0
	v_bfe_u32 v118, v0, 3, 3
	v_lshlrev_b32_e32 v2, 3, v3
	v_lshl_add_u64 v[114:115], s[94:95], 0, v[160:161]
	v_mul_u32_u24_e32 v3, 0x120, v3
	v_and_b32_e32 v160, 0x70, v1
	v_mul_u32_u24_e32 v0, 0x90, v118
	s_lshr_b32 s0, s0, 6
	v_lshlrev_b32_e32 v3, 1, v3
	v_add3_u32 v139, s1, v0, v160
	s_lshl_b32 s41, s42, 3
	v_cmp_lt_u32_e64 s[6:7], v4, v112
	v_add3_u32 v119, s1, v3, v5
	v_add_u32_e32 v123, 0x90, v121
	v_add_u32_e32 v125, 0x120, v121
	v_add_u32_e32 v136, 0x3f0, v121
	v_add_u32_e32 v137, 0x870, v121
	v_add_u32_e32 v138, 0xcf0, v121
	v_lshl_add_u64 v[116:117], s[78:79], 0, v[160:161]
	v_or_b32_e32 v120, 8, v118
	v_or_b32_e32 v122, 16, v118
	v_or_b32_e32 v124, 24, v118
	v_add_u32_e32 v140, 0x480, v139
	v_add_u32_e32 v141, 0x900, v139
	v_add_u32_e32 v142, 0xd80, v139
	s_add_i32 s43, s72, s0
	v_lshlrev_b32_e32 v126, 1, v2
	v_lshlrev_b32_e32 v128, 1, v4
	s_branch .LBB0_524

; __device__ __forceinline__ unsigned xb_ld(unsigned* p)              { return __hip_atomic_load(p, __ATOMIC_RELAXED, __HIP_MEMORY_SCOPE_AGENT); }
; __device__ __forceinline__ unsigned xb_add(unsigned* p, unsigned v) { return __hip_atomic_fetch_add(p, v, __ATOMIC_RELAXED, __HIP_MEMORY_SCOPE_AGENT); }
; template <int DV> DI void la3(const Ctx& c, const bf16* __restrict__ QT, const bf16* __restrict__ KT, const bf16* __restrict__ VT, const bf16* __restrict__ ST, const float* __restrict__ gain, const bf16* __restrict__ gate, int gate_ld, bf16* __restrict__ OUT, int out_col0) {
;     constexpr int NP = (DV / 32) * 2 / 8, NEB = DV / 32;
;     const int l31 = c.lane & 31, hi = c.lane >> 5;
;     unsigned char* QL = c.lds; unsigned char* KL = c.lds + 16384; unsigned char* VL = c.lds + 32768; unsigned char* SL = c.lds + 65536;
;     bf16* Al = (bf16*)(c.lds + 131072);
;     float* SS = (float*)(c.lds + 131072 + 9216);
;     const int eb = (c.wave * NP) >> 1;
;     const int ib1 = c.wave >> 1, jb1 = c.wave & 1;
;     f32x4 gn[4];
; #pragma unroll
;     for (int g = 0; g < 4; ++g) gn[g] = *(const f32x4*)(gain + 32 * eb + 8 * g + 4 * hi);
;     ...
;     La3Stage<DV> stg;
;     if (c.bid < 2048) la3_issue<DV>(stg, QT, KT, VT, ST, c.bid, c.tid);
; __device__ __forceinline__ void xcd_barrier(const XcdBarrier& b) {
;     ...
;         const unsigned old = xb_add(&bar[XB_XSUB(b.x)], 1u);
;         const unsigned gen = old / nloc;
;         if (old + 1u == (gen + 1u) * nloc) {
;             __builtin_amdgcn_fence(__ATOMIC_RELEASE, "agent");
;             asm volatile("s_waitcnt vmcnt(0)" ::: "memory");
;             const unsigned og = xb_add(&bar[XB_TOP], 1u);
;             const unsigned tg = og / nx;
;             if (og + 1u == (tg + 1u) * nx) xb_add(&bar[XB_TOPGEN], 1u);
;             else XB_SPIN(xb_ld(&bar[XB_TOPGEN]) == tg, bar);
;             __builtin_amdgcn_fence(__ATOMIC_ACQUIRE, "agent");
;             xb_add(&bar[XB_XGEN(b.x)], 1u);
;             asm volatile("s_waitcnt vmcnt(0)" ::: "memory");
;         } else {
;             XB_SPIN(xb_ld(&bar[XB_XGEN(b.x)]) == gen, bar);
;             __builtin_amdgcn_fence(__ATOMIC_ACQUIRE, "agent");
;             asm volatile("s_waitcnt vmcnt(0)" ::: "memory");
;         }
;     }
;     __syncthreads();
; }
.Lnb_done_6:
	s_waitcnt vmcnt(0)
.LBB0_596:
	s_or_b64 exec, exec, s[0:1]
	v_readlane_b32 s0, v253, 46
	s_waitcnt lgkmcnt(0)
	v_mov_b32_e32 v0, v186
	v_readlane_b32 s1, v253, 47
	s_barrier
	s_and_b64 vcc, exec, s[0:1]
	v_readfirstlane_b32 s6, v0
	s_cbranch_vccz .LBB0_606
	s_ashr_i32 s0, s6, 7
	s_lshl_b32 s4, s0, 5
	s_ashr_i32 s40, s6, 6
	s_ashr_i32 s5, s4, 31
	v_readlane_b32 s12, v253, 4
	s_and_b32 s1, s40, 1
	s_lshl_b64 s[8:9], s[4:5], 2
	v_readlane_b32 s22, v253, 14
	v_readlane_b32 s23, v253, 15
	s_add_u32 s8, s22, s8
	s_waitcnt vmcnt(13)
	v_bfe_u32 v74, v0, 5, 1
	s_addc_u32 s9, s23, s9
	v_lshlrev_b32_e32 v75, 4, v74
	global_load_dwordx4 v[16:19], v75, s[8:9] offset:96
	global_load_dwordx4 v[20:23], v75, s[8:9] offset:64
	global_load_dwordx4 v[24:27], v75, s[8:9] offset:32
	global_load_dwordx4 v[28:31], v75, s[8:9]
	v_lshlrev_b32_e32 v1, 4, v0
	v_readlane_b32 s8, v254, 0
	v_and_b32_e32 v160, 0xf0, v1
	v_readlane_b32 s9, v254, 1
	v_ashrrev_i32_e32 v6, 4, v0
	v_ashrrev_i32_e32 v7, 31, v6
	v_lshl_add_u64 v[2:3], s[8:9], 0, v[160:161]
	v_readlane_b32 s8, v254, 2
	v_readlane_b32 s9, v254, 3
	s_waitcnt vmcnt(15)
	v_lshlrev_b64 v[80:81], 9, v[6:7]
	v_ashrrev_i32_e32 v1, 31, v0
	v_lshl_add_u64 v[4:5], s[8:9], 0, v[160:161]
	v_readlane_b32 s8, v253, 48
	v_readlane_b32 s9, v253, 49
	s_waitcnt vmcnt(14)
	v_lshlrev_b64 v[84:85], 4, v[0:1]
	v_and_b32_e32 v72, 31, v0
	v_lshl_add_u64 v[8:9], v[80:81], 0, s[8:9]
	v_lshlrev_b64 v[8:9], 1, v[8:9]
	v_lshl_add_u64 v[10:11], v[2:3], 0, v[8:9]
	v_lshl_add_u64 v[8:9], v[4:5], 0, v[8:9]
	global_load_dwordx4 v[32:35], v[10:11], off
	global_load_dwordx4 v[36:39], v[8:9], off
	v_add_u32_e32 v8, 0x200, v0
	v_ashrrev_i32_e32 v10, 4, v8
	v_ashrrev_i32_e32 v11, 31, v10
	v_lshlrev_b64 v[82:83], 9, v[10:11]
	v_lshl_add_u64 v[12:13], v[82:83], 0, s[8:9]
	v_lshlrev_b64 v[12:13], 1, v[12:13]
	v_readlane_b32 s8, v254, 4
	v_ashrrev_i32_e32 v9, 31, v8
	v_lshl_add_u64 v[2:3], v[2:3], 0, v[12:13]
	v_lshl_add_u64 v[4:5], v[4:5], 0, v[12:13]
	v_readlane_b32 s9, v254, 5
	v_lshlrev_b64 v[86:87], 4, v[8:9]
	global_load_dwordx4 v[40:43], v[2:3], off
	global_load_dwordx4 v[44:47], v[4:5], off
	v_lshl_add_u64 v[2:3], s[8:9], 0, v[84:85]
	v_lshl_add_u64 v[4:5], s[8:9], 0, v[86:87]
	v_readlane_b32 s8, v254, 8
	v_readlane_b32 s9, v254, 9
	global_load_dwordx4 v[48:51], v[2:3], off
	global_load_dwordx4 v[52:55], v[4:5], off
	v_lshl_add_u64 v[2:3], s[8:9], 0, v[84:85]
	v_lshl_add_u64 v[4:5], s[8:9], 0, v[86:87]
	global_load_dwordx4 v[56:59], v[2:3], off
	global_load_dwordx4 v[60:63], v[4:5], off
	v_add_u32_e32 v2, 0x400, v0
	v_ashrrev_i32_e32 v3, 31, v2
	v_add_u32_e32 v12, 0x600, v0
	s_waitcnt vmcnt(21)
	v_lshlrev_b64 v[88:89], 4, v[2:3]
	v_ashrrev_i32_e32 v13, 31, v12
	v_lshl_add_u64 v[4:5], s[8:9], 0, v[88:89]
	v_lshlrev_b64 v[90:91], 4, v[12:13]
	v_lshl_add_u64 v[14:15], s[8:9], 0, v[90:91]
	global_load_dwordx4 v[64:67], v[4:5], off
	global_load_dwordx4 v[68:71], v[14:15], off
	s_cmp_le_i32 s1, s0
	v_lshlrev_b32_e32 v3, 8, v72
	s_cselect_b64 s[74:75], -1, 0
	v_lshl_or_b32 v4, s1, 13, v3
	v_lshl_or_b32 v3, s0, 13, v3
	s_add_i32 s43, 0, 0x10000
	v_and_b32_e32 v15, 64, v193
	s_waitcnt vmcnt(18)
; #define MFMA32(a, b, c) __builtin_amdgcn_mfma_f32_32x32x16_bf16((a), (b), (c), 0, 0, 0)
; DI unsigned pk2(float lo, float hi) { return pg8::cvt_pk_bf16(lo, hi); }
; template <int DV> DI void la3(const Ctx& c, const bf16* __restrict__ QT, const bf16* __restrict__ KT, const bf16* __restrict__ VT, const bf16* __restrict__ ST, const float* __restrict__ gain, const bf16* __restrict__ gate, int gate_ld, bf16* __restrict__ OUT, int out_col0) {
;     constexpr int NP = (DV / 32) * 2 / 8, NEB = DV / 32;
;     const int l31 = c.lane & 31, hi = c.lane >> 5;
;     unsigned char* QL = c.lds; unsigned char* KL = c.lds + 16384; unsigned char* VL = c.lds + 32768; unsigned char* SL = c.lds + 65536;
;     bf16* Al = (bf16*)(c.lds + 131072);
;     float* SS = (float*)(c.lds + 131072 + 9216);
;     const int eb = (c.wave * NP) >> 1;
;     const int ib1 = c.wave >> 1, jb1 = c.wave & 1;
;     f32x4 gn[4];
; #pragma unroll
;     for (int g = 0; g < 4; ++g) gn[g] = *(const f32x4*)(gain + 32 * eb + 8 * g + 4 * hi);
;     ...
;     La3Stage<DV> stg;
;     if (c.bid < 2048) la3_issue<DV>(stg, QT, KT, VT, ST, c.bid, c.tid);
;     for (int u = c.bid; u < 2048; u += c.G) {
;         const int cp = u >> 2, h = u & 3; const size_t row0 = (size_t)cp * 64;
;         la3_commit<DV>(stg, c.lds, c.tid);
;         __syncthreads();
;         if (c.wave < 4) {
;             f32x16 acc; for (int r = 0; r < 16; ++r) acc[r] = 0.f;
;             if (jb1 <= ib1) {
; #pragma unroll
;                 for (int kk = 0; kk < 8; ++kk) acc = MFMA32(LA3_F256(KL, 32 * jb1 + l31, kk), LA3_F256(QL, 32 * ib1 + l31, kk), acc);
;             }
; #pragma unroll
;             for (int g = 0; g < 4; ++g) { float v[4];
; #pragma unroll
;                 for (int x = 0; x < 4; ++x) { const int j = 32 * jb1 + 8 * g + 4 * hi + x, i = 32 * ib1 + l31; v[x] = (j <= i) ? acc[4 * g + x] : 0.f; }
;                 u32x2 w; w.x = pk2(v[0], v[1]); w.y = pk2(v[2], v[3]);
;                 *(u32x2*)(Al + (32 * ib1 + l31) * 72 + 32 * jb1 + 8 * g + 4 * hi) = w; }
	v_add_u32_e32 v109, 0, v3
	v_add_u32_e32 v111, s43, v3
	v_xor_b32_e32 v3, 32, v193
	v_add_u32_e32 v15, 64, v15
	v_cmp_lt_i32_e32 vcc, v3, v15
	v_add_u32_e32 v108, 0, v4
	v_and_b32_e32 v4, 15, v0
	v_cndmask_b32_e32 v3, v193, v3, vcc
	v_lshlrev_b32_e32 v112, 2, v3
	v_bitop3_b32 v3, v74, v0, 15 bitop3:0x78
	v_lshlrev_b32_e32 v113, 4, v3
	v_bitop3_b32 v3, v74, v4, 2 bitop3:0x36
	v_lshlrev_b32_e32 v114, 4, v3
	v_bitop3_b32 v3, v74, v4, 4 bitop3:0x36
	v_lshlrev_b32_e32 v115, 4, v3
	v_bitop3_b32 v3, v74, v4, 6 bitop3:0x36
	v_lshlrev_b32_e32 v116, 4, v3
	v_bitop3_b32 v3, v74, v4, 8 bitop3:0x36
	v_lshlrev_b32_e32 v117, 4, v3
	v_bitop3_b32 v3, v74, v4, 10 bitop3:0x36
	s_lshl_b32 s41, s1, 5
	v_lshlrev_b32_e32 v118, 4, v3
	v_bitop3_b32 v3, v74, v4, 12 bitop3:0x36
	v_lshl_or_b32 v5, v74, 2, s41
	v_lshlrev_b32_e32 v119, 4, v3
	v_bitop3_b32 v3, v74, v4, 14 bitop3:0x36
	v_or_b32_e32 v7, s4, v72
	v_lshlrev_b32_e32 v120, 4, v3
	v_or_b32_e32 v3, 2, v5
	v_readlane_b32 s13, v253, 5
	v_cmp_gt_i32_e64 s[10:11], v3, v7
	v_or_b32_e32 v3, 3, v5
	v_readlane_b32 s14, v253, 6
	v_readlane_b32 s15, v253, 7
	v_cmp_gt_i32_e64 s[12:13], v3, v7
	v_or_b32_e32 v3, 8, v5
	v_readlane_b32 s16, v253, 8
	v_readlane_b32 s17, v253, 9
	v_cmp_gt_i32_e64 s[14:15], v3, v7
	v_or_b32_e32 v3, 9, v5
	v_readlane_b32 s18, v253, 10
	v_readlane_b32 s19, v253, 11
	v_cmp_gt_i32_e64 s[16:17], v3, v7
	v_or_b32_e32 v3, 10, v5
	v_readlane_b32 s20, v253, 12
	v_readlane_b32 s21, v253, 13
	v_cmp_gt_i32_e64 s[18:19], v3, v7
	v_or_b32_e32 v3, 11, v5
	v_cmp_gt_i32_e64 s[20:21], v3, v7
	v_or_b32_e32 v3, 16, v5
	v_readlane_b32 s24, v253, 16
	v_readlane_b32 s25, v253, 17
	v_cmp_gt_i32_e64 s[22:23], v3, v7
	v_or_b32_e32 v3, 17, v5
	v_readlane_b32 s26, v253, 18
	v_readlane_b32 s27, v253, 19
	v_cmp_gt_i32_e64 s[24:25], v3, v7
	v_or_b32_e32 v3, 18, v5
	s_movk_i32 s2, 0x90
	s_add_i32 s4, 0, 0x20000
	s_lshl_b32 s5, s1, 6
	v_cmp_gt_i32_e64 s[26:27], v3, v7
	v_or_b32_e32 v3, 19, v5
	v_mul_lo_u32 v11, v7, s2
	s_add_i32 s5, s5, s4
	v_lshlrev_b32_e32 v13, 3, v74
	v_cmp_gt_i32_e64 s[28:29], v3, v7
	v_or_b32_e32 v3, 24, v5
	v_add3_u32 v110, s5, v11, v13
	v_add_u32_e32 v11, s4, v75
	s_lshl_b32 s4, s0, 12
	v_cmp_gt_i32_e64 s[30:31], v3, v7
	v_or_b32_e32 v3, 25, v5
	v_lshrrev_b32_e32 v1, 28, v1
	s_add_i32 s4, s4, 0
	s_and_b32 s52, s6, 0xffffff80
	v_cmp_gt_i32_e64 s[34:35], v3, v7
	v_or_b32_e32 v3, 26, v5
	v_add_u32_e32 v1, v0, v1
	v_and_b32_e32 v14, 7, v0
	v_cmp_gt_i32_e64 s[36:37], v3, v7
	v_or_b32_e32 v3, 27, v5
	v_ashrrev_i32_e32 v77, 3, v0
	v_ashrrev_i32_e32 v79, 3, v8
	v_ashrrev_i32_e32 v2, 4, v2
	v_ashrrev_i32_e32 v12, 4, v12
	s_cmp_lt_i32 s40, 4
	v_ashrrev_i32_e32 v92, 4, v1
	v_and_b32_e32 v1, -16, v1
	v_and_b32_e32 v73, 63, v0
	v_cmp_gt_i32_e64 s[6:7], v5, v7
	v_cmp_lt_i32_e64 s[8:9], v5, v7
	v_cmp_gt_i32_e64 s[38:39], v3, v7
	v_bitop3_b32 v3, v74, v0, 7 bitop3:0x78
	v_bitop3_b32 v4, v74, v14, 2 bitop3:0x36
	v_bitop3_b32 v5, v74, v14, 4 bitop3:0x36
	v_bitop3_b32 v7, v74, v14, 6 bitop3:0x36
	v_lshlrev_b32_e32 v14, 8, v6
	v_xor_b32_e32 v6, v6, v0
	v_lshlrev_b32_e32 v74, 8, v10
	v_xor_b32_e32 v10, v10, v0
	v_lshl_add_u32 v78, v77, 7, 0
	v_xor_b32_e32 v77, v77, v0
	v_lshl_add_u32 v104, v79, 7, 0
	v_xor_b32_e32 v79, v79, v0
	v_lshl_add_u32 v105, v2, 8, s43
	v_xor_b32_e32 v2, v2, v0
	v_lshl_add_u32 v106, v12, 8, s43
	v_xor_b32_e32 v12, v12, v0
	s_cselect_b64 s[80:81], -1, 0
	v_sub_u32_e32 v0, v0, v1
	v_lshrrev_b32_e32 v1, 28, v9
	s_lshl_b32 s40, s40, 5
	v_add_u32_e32 v1, v8, v1
	v_and_or_b32 v9, s40, 32, v72
	v_readlane_b32 s2, v254, 44
	v_lshlrev_b32_e32 v6, 4, v6
	v_lshlrev_b32_e32 v10, 4, v10
	v_ashrrev_i32_e32 v96, 4, v1
	v_and_b32_e32 v1, -16, v1
	v_lshl_add_u32 v121, v9, 2, s2
	v_mul_u32_u24_e32 v9, 0x210, v9
	s_movk_i32 s40, 0x210
	s_lshl_b32 s1, s1, 7
	v_lshl_add_u32 v13, v72, 7, s4
	v_and_b32_e32 v6, 0xf0, v6
	v_and_b32_e32 v10, 0xf0, v10
	v_lshlrev_b32_e32 v77, 4, v77
	v_lshlrev_b32_e32 v79, 4, v79
	v_lshlrev_b32_e32 v2, 4, v2
	v_lshlrev_b32_e32 v12, 4, v12
	v_sub_u32_e32 v1, v8, v1
	v_or_b32_e32 v8, s41, v72
	v_readlane_b32 s66, v253, 62
	v_add3_u32 v9, s43, v9, v75
	v_mul_lo_u32 v72, v92, s40
	v_mul_lo_u32 v75, v96, s40
	s_add_i32 s1, s2, s1
	s_lshl_b32 s0, s0, 8
	v_lshlrev_b32_e32 v3, 4, v3
	v_lshlrev_b32_e32 v4, 4, v4
	v_lshlrev_b32_e32 v5, 4, v5
	v_lshlrev_b32_e32 v7, 4, v7
	v_or_b32_e32 v15, v6, v14
	v_or_b32_e32 v76, v10, v74
	v_and_b32_e32 v77, 0x70, v77
	v_and_b32_e32 v79, 0x70, v79
	v_add_u32_e32 v14, s43, v14
	v_add_u32_e32 v74, s43, v74
	v_and_b32_e32 v2, 0xf0, v2
	v_and_b32_e32 v12, 0xf0, v12
	v_lshlrev_b32_e32 v94, 3, v0
	v_lshlrev_b32_e32 v98, 3, v1
	v_mul_u32_u24_e32 v8, 0x90, v8
	v_readlane_b32 s67, v253, 63
	v_add_u32_e32 v72, s43, v72
	v_lshlrev_b32_e32 v0, 5, v0
	v_add_u32_e32 v75, s43, v75
	v_lshlrev_b32_e32 v1, 5, v1
	s_add_i32 s1, s1, s0
	s_mov_b32 s86, 0xf800000
	v_cmp_gt_u32_e64 s[4:5], 32, v73
	v_ashrrev_i32_e32 v93, 31, v92
	v_ashrrev_i32_e32 v95, 31, v94
	v_ashrrev_i32_e32 v97, 31, v96
	v_ashrrev_i32_e32 v99, 31, v98
	v_lshl_add_u64 v[100:101], s[66:67], 0, v[160:161]
	v_lshl_add_u64 v[102:103], s[76:77], 0, v[160:161]
	v_lshl_add_u32 v122, v73, 2, s1
	s_lshl_b32 s43, s42, 7
	v_add_u32_e32 v123, 0, v15
	v_add_u32_e32 v124, 0, v76
	v_add_u32_e32 v125, v78, v77
	v_add_u32_e32 v126, v104, v79
	v_add_u32_e32 v127, v14, v6
	v_add_u32_e32 v128, v74, v10
	v_add_u32_e32 v129, v105, v2
	v_add_u32_e32 v130, v106, v12
	v_add_u32_e32 v131, v11, v8
	v_add_u32_e32 v132, v13, v3
	v_add_u32_e32 v133, v13, v4
	v_add_u32_e32 v134, v13, v5
	v_add_u32_e32 v135, v13, v7
	v_add_u32_e32 v136, s52, v9
	v_add_u32_e32 v137, v72, v0
	v_add_u32_e32 v138, v75, v1
	v_readlane_b32 s89, v253, 50
	s_mov_b32 s67, s90
	s_branch .LBB0_599

; __device__ __forceinline__ unsigned xb_ld(unsigned* p)              { return __hip_atomic_load(p, __ATOMIC_RELAXED, __HIP_MEMORY_SCOPE_AGENT); }
; __device__ __forceinline__ unsigned xb_add(unsigned* p, unsigned v) { return __hip_atomic_fetch_add(p, v, __ATOMIC_RELAXED, __HIP_MEMORY_SCOPE_AGENT); }
; #define XB_SPIN(cond, bar) do { unsigned _sp = 0; while (cond) { __builtin_amdgcn_s_sleep(1); \
;     if ((++_sp & 255u) == 0u) { if (xb_ld(&(bar)[XB_TMO])) break; if (_sp > XB_SPIN_CAP) { atomicAdd(&(bar)[XB_TMO], 1u); break; } } } } while (0)
; __device__ __forceinline__ void xcd_barrier(const XcdBarrier& b) {
;     asm volatile("s_waitcnt vmcnt(0)" ::: "memory");
;     __syncthreads();
;     if (threadIdx.x == 0) {
;         unsigned* bar = b.bar;
;         __builtin_amdgcn_s_waitcnt(0);
;         unsigned nloc = b.st[0], nx = b.st[1];
;         if (nloc == 0u) { xcd_barrier_complete(bar, b.x, nloc, nx); b.st[0] = nloc; b.st[1] = nx; }
;         const unsigned old = xb_add(&bar[XB_XSUB(b.x)], 1u);
;         const unsigned gen = old / nloc;
;         if (old + 1u == (gen + 1u) * nloc) {
;             __builtin_amdgcn_fence(__ATOMIC_RELEASE, "agent");
;             asm volatile("s_waitcnt vmcnt(0)" ::: "memory");
;             const unsigned og = xb_add(&bar[XB_TOP], 1u);
;             const unsigned tg = og / nx;
;             if (og + 1u == (tg + 1u) * nx) xb_add(&bar[XB_TOPGEN], 1u);
;             else XB_SPIN(xb_ld(&bar[XB_TOPGEN]) == tg, bar);
;             __builtin_amdgcn_fence(__ATOMIC_ACQUIRE, "agent");
;             xb_add(&bar[XB_XGEN(b.x)], 1u);
;             asm volatile("s_waitcnt vmcnt(0)" ::: "memory");
;         } else {
;             XB_SPIN(xb_ld(&bar[XB_XGEN(b.x)]) == gen, bar);
;             __builtin_amdgcn_fence(__ATOMIC_ACQUIRE, "agent");
;             asm volatile("s_waitcnt vmcnt(0)" ::: "memory");
;         }
;     }
;     __syncthreads();
; }
.LBB0_606:
	s_getreg_b32 s4, hwreg(HW_REG_XCC_ID, 0, 4)
	s_waitcnt vmcnt(0)
	s_barrier
	s_and_saveexec_b64 s[0:1], s[68:69]
	s_xor_b64 s[0:1], exec, s[0:1]
	s_cbranch_execz .LBB0_659
	v_readlane_b32 s2, v254, 42
	s_waitcnt vmcnt(0) expcnt(0) lgkmcnt(0)
	buffer_inv sc1
	s_and_b32 s10, s4, 15
	s_lshl_b32 s5, s10, 8
	v_mov_b32_e32 v0, s2
	ds_read_b32 v2, v0
	v_readlane_b32 s2, v254, 43
	s_add_u32 s12, s46, s5
	s_addc_u32 s13, s47, 0
	v_mov_b32_e32 v3, 1
	v_mov_b32_e32 v0, s2
	ds_read_b32 v6, v0
	v_mov_b32_e32 v5, 0x1400
	s_waitcnt lgkmcnt(0)
	global_atomic_add v3, v5, v3, s[12:13] sc0
	v_cvt_f32_u32_e32 v4, v2
	s_waitcnt vmcnt(0)
	v_mov_b32_e32 v5, v3
	v_sub_u32_e32 v3, 0, v2
	v_rcp_iflag_f32_e32 v4, v4
	s_nop 0
	v_mul_f32_e32 v4, 0x4f7ffffe, v4
	v_cvt_u32_f32_e32 v4, v4
	v_mul_lo_u32 v1, v3, v4
	v_mul_hi_u32 v1, v4, v1
	v_add_u32_e32 v1, v4, v1
	v_mul_hi_u32 v1, v5, v1
	v_mul_lo_u32 v3, v1, v2
	v_sub_u32_e32 v3, v5, v3
	v_add_u32_e32 v4, 1, v1
	v_cmp_ge_u32_e32 vcc, v3, v2
	s_nop 1
	v_cndmask_b32_e32 v1, v1, v4, vcc
	v_sub_u32_e32 v4, v3, v2
	v_cndmask_b32_e32 v3, v3, v4, vcc
	v_add_u32_e32 v4, 1, v1
	v_cmp_ge_u32_e32 vcc, v3, v2
	v_add_u32_e32 v3, 1, v5
	s_nop 0
	v_cndmask_b32_e32 v1, v1, v4, vcc
	v_mul_lo_u32 v4, v2, v1
	v_add_u32_e32 v2, v4, v2
	v_mul_lo_u32 v7, v1, v6
	v_cmp_ne_u32_e32 vcc, v3, v2
	s_mov_b32 s8, 0
	s_cbranch_vccnz .Lnb_loop_7
	buffer_wbl2 sc1
	v_mov_b32_e32 v8, 1
	v_mov_b32_e32 v9, 0x2404
	s_waitcnt vmcnt(0)
	global_atomic_add v9, v8, s[46:47]
	v_add_u32_e32 v9, 0x100, v9
	global_atomic_add v9, v8, s[46:47]
	v_add_u32_e32 v9, 0x100, v9
	global_atomic_add v9, v8, s[46:47]
	v_add_u32_e32 v9, 0x100, v9
	global_atomic_add v9, v8, s[46:47]
	v_add_u32_e32 v9, 0x100, v9
	global_atomic_add v9, v8, s[46:47]
	v_add_u32_e32 v9, 0x100, v9
	global_atomic_add v9, v8, s[46:47]
	v_add_u32_e32 v9, 0x100, v9
	global_atomic_add v9, v8, s[46:47]
	v_add_u32_e32 v9, 0x100, v9
	global_atomic_add v9, v8, s[46:47]
	v_add_u32_e32 v9, 0x100, v9
	global_atomic_add v9, v8, s[46:47]
	v_add_u32_e32 v9, 0x100, v9
	global_atomic_add v9, v8, s[46:47]
	v_add_u32_e32 v9, 0x100, v9
	global_atomic_add v9, v8, s[46:47]
	v_add_u32_e32 v9, 0x100, v9
	global_atomic_add v9, v8, s[46:47]
	v_add_u32_e32 v9, 0x100, v9
	global_atomic_add v9, v8, s[46:47]
	v_add_u32_e32 v9, 0x100, v9
	global_atomic_add v9, v8, s[46:47]
	v_add_u32_e32 v9, 0x100, v9
	global_atomic_add v9, v8, s[46:47]
	v_add_u32_e32 v9, 0x100, v9
	global_atomic_add v9, v8, s[46:47]

; __device__ __forceinline__ unsigned xb_ld(unsigned* p)              { return __hip_atomic_load(p, __ATOMIC_RELAXED, __HIP_MEMORY_SCOPE_AGENT); }
; __device__ __forceinline__ unsigned xb_add(unsigned* p, unsigned v) { return __hip_atomic_fetch_add(p, v, __ATOMIC_RELAXED, __HIP_MEMORY_SCOPE_AGENT); }
; #define XB_SPIN(cond, bar) do { unsigned _sp = 0; while (cond) { __builtin_amdgcn_s_sleep(1); \
;     if ((++_sp & 255u) == 0u) { if (xb_ld(&(bar)[XB_TMO])) break; if (_sp > XB_SPIN_CAP) { atomicAdd(&(bar)[XB_TMO], 1u); break; } } } } while (0)
; __device__ __forceinline__ void xcd_barrier(const XcdBarrier& b) {
;     ...
;         const unsigned old = xb_add(&bar[XB_XSUB(b.x)], 1u);
;         const unsigned gen = old / nloc;
;         if (old + 1u == (gen + 1u) * nloc) {
;             __builtin_amdgcn_fence(__ATOMIC_RELEASE, "agent");
;             asm volatile("s_waitcnt vmcnt(0)" ::: "memory");
;             const unsigned og = xb_add(&bar[XB_TOP], 1u);
;             const unsigned tg = og / nx;
;             if (og + 1u == (tg + 1u) * nx) xb_add(&bar[XB_TOPGEN], 1u);
;             else XB_SPIN(xb_ld(&bar[XB_TOPGEN]) == tg, bar);
;             __builtin_amdgcn_fence(__ATOMIC_ACQUIRE, "agent");
;             xb_add(&bar[XB_XGEN(b.x)], 1u);
;             asm volatile("s_waitcnt vmcnt(0)" ::: "memory");
;         } else {
;             XB_SPIN(xb_ld(&bar[XB_XGEN(b.x)]) == gen, bar);
;             __builtin_amdgcn_fence(__ATOMIC_ACQUIRE, "agent");
;             asm volatile("s_waitcnt vmcnt(0)" ::: "memory");
;         }
;     }
;     __syncthreads();
; }
.Lnb_done_7:
	s_waitcnt vmcnt(0)
.LBB0_659:
	s_or_b64 exec, exec, s[0:1]
	v_readlane_b32 s8, v253, 4
	v_readlane_b32 s9, v253, 5
	s_waitcnt lgkmcnt(0)
	s_barrier
	s_mov_b64 s[4:5], 0x900000
	v_readlane_b32 s10, v253, 6
	v_readlane_b32 s11, v253, 7
	v_readlane_b32 s12, v253, 8
	v_readlane_b32 s13, v253, 9
	v_readlane_b32 s14, v253, 10
	v_readlane_b32 s15, v253, 11
	v_readlane_b32 s16, v253, 12
	v_readlane_b32 s17, v253, 13
	v_readlane_b32 s18, v253, 14
	v_readlane_b32 s19, v253, 15
	v_readlane_b32 s20, v253, 16
	v_readlane_b32 s21, v253, 17
	v_readlane_b32 s22, v253, 18
	v_readlane_b32 s23, v253, 19
	s_mov_b64 s[0:1], s[8:9]
	s_mov_b64 s[42:43], 0x3400

; DI void norm_phase(const Ctx& c, const float* __restrict__ h, const float* __restrict__ g, bf16* __restrict__ xn) {
;     const f32x4* gr = (const f32x4*)g + c.lane;
;     f32x4 gg[4];
; #pragma unroll
;     for (int j = 0; j < 4; ++j) gg[j] = gr[64 * j];
;     for (int m0 = c.gw * 4; m0 < M; m0 += c.NGW * 4) {
;         f32x4 v[4][4];
; #pragma unroll
;         for (int r = 0; r < 4; ++r) { const f32x4* xr = (const f32x4*)(h + (size_t)(m0 + r) * D) + c.lane;
; #pragma unroll
;             for (int j = 0; j < 4; ++j) v[r][j] = __builtin_nontemporal_load(xr + 64 * j); }
; #pragma unroll
;         for (int r = 0; r < 4; ++r) {
;             float s = 0.f;
; #pragma unroll
;             for (int j = 0; j < 4; ++j) s += (v[r][j].x * v[r][j].x + v[r][j].y * v[r][j].y) + (v[r][j].z * v[r][j].z + v[r][j].w * v[r][j].w);
;             const float rstd = 1.f / sqrtf(wave_sum(s) * (1.f / 1024.f) + 1e-6f);
; __device__ __forceinline__ void xcd_barrier(const XcdBarrier& b) {
;     asm volatile("s_waitcnt vmcnt(0)" ::: "memory");
;     __syncthreads();
;     if (threadIdx.x == 0) {
;         unsigned* bar = b.bar;
;         __builtin_amdgcn_s_waitcnt(0);
;         unsigned nloc = b.st[0], nx = b.st[1];
;         if (nloc == 0u) { xcd_barrier_complete(bar, b.x, nloc, nx); b.st[0] = nloc; b.st[1] = nx; }
;         const unsigned old = xb_add(&bar[XB_XSUB(b.x)], 1u);
;         const unsigned gen = old / nloc;
;         if (old + 1u == (gen + 1u) * nloc) {
;             __builtin_amdgcn_fence(__ATOMIC_RELEASE, "agent");
;             asm volatile("s_waitcnt vmcnt(0)" ::: "memory");
;             const unsigned og = xb_add(&bar[XB_TOP], 1u);
;             const unsigned tg = og / nx;
;             if (og + 1u == (tg + 1u) * nx) xb_add(&bar[XB_TOPGEN], 1u);
;             else XB_SPIN(xb_ld(&bar[XB_TOPGEN]) == tg, bar);
;             __builtin_amdgcn_fence(__ATOMIC_ACQUIRE, "agent");
;             xb_add(&bar[XB_XGEN(b.x)], 1u);
;             asm volatile("s_waitcnt vmcnt(0)" ::: "memory");
;         } else {
;             XB_SPIN(xb_ld(&bar[XB_XGEN(b.x)]) == gen, bar);
;             __builtin_amdgcn_fence(__ATOMIC_ACQUIRE, "agent");
;             asm volatile("s_waitcnt vmcnt(0)" ::: "memory");
;         }
;     }
;     __syncthreads();
; }
.Lnb_done_8:
	s_waitcnt vmcnt(0)
.LBB0_733:
	s_or_b64 exec, exec, s[0:1]
	s_waitcnt lgkmcnt(0)
	v_mov_b32_e32 v0, v186
	s_barrier
	s_nop 0
	v_readfirstlane_b32 s0, v0
	s_ashr_i32 s0, s0, 6
	s_add_i32 s0, s0, s72
	s_cmpk_lt_i32 s0, 0x2000
	s_cbranch_scc0 .LBB0_736
	s_lshl_b32 s2, s64, 10
	v_readlane_b32 s8, v253, 20
	s_lshl_b64 s[4:5], s[2:3], 2
	v_readlane_b32 s16, v253, 28
	v_readlane_b32 s17, v253, 29
	s_add_u32 s4, s16, s4
	v_and_b32_e32 v16, 63, v0
	s_addc_u32 s5, s17, s5
	v_lshlrev_b32_e32 v160, 4, v16
	global_load_dwordx4 v[0:3], v160, s[4:5] offset:3072
	global_load_dwordx4 v[4:7], v160, s[4:5] offset:2048
	global_load_dwordx4 v[8:11], v160, s[4:5] offset:1024
	global_load_dwordx4 v[12:15], v160, s[4:5]
	v_and_b32_e32 v17, 64, v193
	v_add_u32_e32 v17, 64, v17
	v_xor_b32_e32 v18, 1, v193
	v_cmp_lt_i32_e32 vcc, v18, v17
	s_load_dword s1, s[70:71], 0x0
	s_lshl_b32 s6, s0, 2
	v_cndmask_b32_e32 v18, v193, v18, vcc
	s_waitcnt vmcnt(15)
	v_lshlrev_b32_e32 v81, 2, v18
	v_xor_b32_e32 v18, 2, v193
	v_cmp_lt_i32_e32 vcc, v18, v17
	s_ashr_i32 s7, s6, 31
	s_waitcnt lgkmcnt(0)
	s_lshl_b32 s4, s1, 5
	v_cndmask_b32_e32 v18, v193, v18, vcc
	s_waitcnt vmcnt(14)
	v_lshlrev_b32_e32 v84, 2, v18
	v_xor_b32_e32 v18, 4, v193
	v_cmp_lt_i32_e32 vcc, v18, v17
	s_lshl_b64 s[0:1], s[6:7], 11
	v_readlane_b32 s2, v254, 38
	v_cndmask_b32_e32 v18, v193, v18, vcc
	v_lshlrev_b32_e32 v85, 2, v18
	v_xor_b32_e32 v18, 8, v193
	v_cmp_lt_i32_e32 vcc, v18, v17
	s_add_u32 s0, s2, s0
	v_readlane_b32 s2, v254, 39
	v_cndmask_b32_e32 v18, v193, v18, vcc
	v_lshlrev_b32_e32 v86, 2, v18
	v_xor_b32_e32 v18, 16, v193
	v_cmp_lt_i32_e32 vcc, v18, v17
	v_readlane_b32 s9, v253, 21
	v_lshlrev_b32_e32 v16, 3, v16
	v_cndmask_b32_e32 v18, v193, v18, vcc
	v_lshlrev_b32_e32 v87, 2, v18
	v_xor_b32_e32 v18, 32, v193
	v_cmp_lt_i32_e32 vcc, v18, v17
	s_addc_u32 s1, s2, s1
	s_ashr_i32 s5, s4, 31
	v_cndmask_b32_e32 v17, v193, v18, vcc
	s_waitcnt vmcnt(13)
	v_lshlrev_b32_e32 v88, 2, v17
	v_mov_b32_e32 v17, v161
	v_lshl_add_u64 v[76:77], s[0:1], 0, v[16:17]
	s_lshl_b64 s[8:9], s[4:5], 11
	s_lshl_b64 s[0:1], s[6:7], 12
	v_readlane_b32 s2, v254, 40
	s_add_u32 s0, s2, s0
	v_readlane_b32 s2, v254, 41
	v_readlane_b32 s10, v253, 22
	v_readlane_b32 s11, v253, 23
	s_addc_u32 s1, s2, s1
	v_lshl_add_u64 v[78:79], s[0:1], 0, v[160:161]
	s_lshl_b64 s[10:11], s[4:5], 12
	s_movk_i32 s2, 0xf000
	v_readlane_b32 s12, v253, 24
	v_readlane_b32 s13, v253, 25
	v_readlane_b32 s14, v253, 26
	v_readlane_b32 s15, v253, 27
	v_readlane_b32 s18, v253, 30
	v_readlane_b32 s19, v253, 31
	v_readlane_b32 s20, v253, 32
	v_readlane_b32 s21, v253, 33
	v_readlane_b32 s22, v253, 34
	v_readlane_b32 s23, v253, 35

; __device__ __forceinline__ unsigned xb_ld(unsigned* p)              { return __hip_atomic_load(p, __ATOMIC_RELAXED, __HIP_MEMORY_SCOPE_AGENT); }
; __device__ __forceinline__ unsigned xb_add(unsigned* p, unsigned v) { return __hip_atomic_fetch_add(p, v, __ATOMIC_RELAXED, __HIP_MEMORY_SCOPE_AGENT); }
; #define XB_SPIN(cond, bar) do { unsigned _sp = 0; while (cond) { __builtin_amdgcn_s_sleep(1); \
;     if ((++_sp & 255u) == 0u) { if (xb_ld(&(bar)[XB_TMO])) break; if (_sp > XB_SPIN_CAP) { atomicAdd(&(bar)[XB_TMO], 1u); break; } } } } while (0)
; #define REP(bit) for (int rep_ = 0; rep_ < (((DUP) & (bit)) ? 2 : 1); ++rep_)
; __device__ __forceinline__ void xcd_barrier(const XcdBarrier& b) {
;     asm volatile("s_waitcnt vmcnt(0)" ::: "memory");
;     __syncthreads();
;     if (threadIdx.x == 0) {
;         unsigned* bar = b.bar;
;         __builtin_amdgcn_s_waitcnt(0);
;         unsigned nloc = b.st[0], nx = b.st[1];
;         if (nloc == 0u) { xcd_barrier_complete(bar, b.x, nloc, nx); b.st[0] = nloc; b.st[1] = nx; }
;         const unsigned old = xb_add(&bar[XB_XSUB(b.x)], 1u);
;         const unsigned gen = old / nloc;
;         if (old + 1u == (gen + 1u) * nloc) {
;             __builtin_amdgcn_fence(__ATOMIC_RELEASE, "agent");
;             asm volatile("s_waitcnt vmcnt(0)" ::: "memory");
;             const unsigned og = xb_add(&bar[XB_TOP], 1u);
;             const unsigned tg = og / nx;
;             if (og + 1u == (tg + 1u) * nx) xb_add(&bar[XB_TOPGEN], 1u);
;             else XB_SPIN(xb_ld(&bar[XB_TOPGEN]) == tg, bar);
;             __builtin_amdgcn_fence(__ATOMIC_ACQUIRE, "agent");
;             xb_add(&bar[XB_XGEN(b.x)], 1u);
;             asm volatile("s_waitcnt vmcnt(0)" ::: "memory");
;         } else {
;             XB_SPIN(xb_ld(&bar[XB_XGEN(b.x)]) == gen, bar);
;             __builtin_amdgcn_fence(__ATOMIC_ACQUIRE, "agent");
;             asm volatile("s_waitcnt vmcnt(0)" ::: "memory");
;         }
;     }
;     __syncthreads();
; }
; __global__ void __launch_bounds__(NTHR, 2) fwd_megakernel(Args args) {
;     ...
;         if constexpr (PH & 1024) REP(1024) { pg8::EpiConvGate E{(pg8::bf16_t*)ACT, args.in[14] + (size_t)layer * 3 * DFF, args.in[15] + (size_t)layer * DFF, M};
;           GEMM_PHASE(pg8::EpiConvGate, E, XN - 2 * 1024, ws + (even ? WS_WUP0 : WS_WUP1), 133, 22, 1024, 1); }
.Lnb_done_9:
	s_waitcnt vmcnt(0)
.LBB0_789:
	s_or_b64 exec, exec, s[0:1]
	s_waitcnt lgkmcnt(0)
	s_barrier
	s_load_dword s34, s[70:71], 0x0
	v_readlane_b32 s4, v254, 12
	v_mov_b32_e32 v14, v186
	v_readlane_b32 s5, v254, 13
	s_and_b64 vcc, exec, s[4:5]
	v_readfirstlane_b32 s0, v14
	s_cbranch_vccz .LBB0_791
	v_readlane_b32 s1, v254, 36
	s_mov_b32 s26, s1
	v_readlane_b32 s80, v254, 32

; __device__ __forceinline__ unsigned xb_ld(unsigned* p)              { return __hip_atomic_load(p, __ATOMIC_RELAXED, __HIP_MEMORY_SCOPE_AGENT); }
; __device__ __forceinline__ unsigned xb_add(unsigned* p, unsigned v) { return __hip_atomic_fetch_add(p, v, __ATOMIC_RELAXED, __HIP_MEMORY_SCOPE_AGENT); }
; #define XB_SPIN(cond, bar) do { unsigned _sp = 0; while (cond) { __builtin_amdgcn_s_sleep(1); \
;     if ((++_sp & 255u) == 0u) { if (xb_ld(&(bar)[XB_TMO])) break; if (_sp > XB_SPIN_CAP) { atomicAdd(&(bar)[XB_TMO], 1u); break; } } } } while (0)
; __device__ __forceinline__ void xcd_barrier(const XcdBarrier& b) {
;     asm volatile("s_waitcnt vmcnt(0)" ::: "memory");
;     __syncthreads();
;     if (threadIdx.x == 0) {
;         unsigned* bar = b.bar;
;         __builtin_amdgcn_s_waitcnt(0);
;         unsigned nloc = b.st[0], nx = b.st[1];
;         if (nloc == 0u) { xcd_barrier_complete(bar, b.x, nloc, nx); b.st[0] = nloc; b.st[1] = nx; }
;         const unsigned old = xb_add(&bar[XB_XSUB(b.x)], 1u);
;         const unsigned gen = old / nloc;
;         if (old + 1u == (gen + 1u) * nloc) {
;             __builtin_amdgcn_fence(__ATOMIC_RELEASE, "agent");
;             asm volatile("s_waitcnt vmcnt(0)" ::: "memory");
;             const unsigned og = xb_add(&bar[XB_TOP], 1u);
;             const unsigned tg = og / nx;
;             if (og + 1u == (tg + 1u) * nx) xb_add(&bar[XB_TOPGEN], 1u);
;             else XB_SPIN(xb_ld(&bar[XB_TOPGEN]) == tg, bar);
;             __builtin_amdgcn_fence(__ATOMIC_ACQUIRE, "agent");
;             xb_add(&bar[XB_XGEN(b.x)], 1u);
;             asm volatile("s_waitcnt vmcnt(0)" ::: "memory");
;         } else {
;             XB_SPIN(xb_ld(&bar[XB_XGEN(b.x)]) == gen, bar);
;             __builtin_amdgcn_fence(__ATOMIC_ACQUIRE, "agent");
;             asm volatile("s_waitcnt vmcnt(0)" ::: "memory");
;         }
;     }
;     __syncthreads();
; }
.LBB0_829:
	s_getreg_b32 s4, hwreg(HW_REG_XCC_ID, 0, 4)
	s_waitcnt vmcnt(0)
	s_waitcnt vmcnt(0) lgkmcnt(0)
	s_barrier
	s_and_saveexec_b64 s[0:1], s[68:69]
	v_readlane_b32 s26, v254, 49
	v_readlane_b32 s80, v254, 51
	s_xor_b64 s[0:1], exec, s[0:1]
	v_readlane_b32 s27, v254, 50
	v_readlane_b32 s81, v254, 52
	s_cbranch_execz .LBB0_882
	v_readlane_b32 s2, v254, 42
	s_waitcnt vmcnt(0) expcnt(0) lgkmcnt(0)
	buffer_inv sc1
	s_and_b32 s10, s4, 15
	s_lshl_b32 s5, s10, 8
	v_mov_b32_e32 v0, s2
	ds_read_b32 v2, v0
	v_readlane_b32 s2, v254, 43
	s_add_u32 s12, s46, s5
	s_addc_u32 s13, s47, 0
	v_mov_b32_e32 v3, 1
	v_mov_b32_e32 v0, s2
	ds_read_b32 v6, v0
	v_mov_b32_e32 v5, 0x1400
	s_waitcnt lgkmcnt(0)
	global_atomic_add v3, v5, v3, s[12:13] sc0
	v_cvt_f32_u32_e32 v4, v2
	s_waitcnt vmcnt(0)
	v_mov_b32_e32 v5, v3
	v_sub_u32_e32 v3, 0, v2
	v_rcp_iflag_f32_e32 v4, v4
	s_nop 0
	v_mul_f32_e32 v4, 0x4f7ffffe, v4
	v_cvt_u32_f32_e32 v4, v4
	v_mul_lo_u32 v1, v3, v4
	v_mul_hi_u32 v1, v4, v1
	v_add_u32_e32 v1, v4, v1
	v_mul_hi_u32 v1, v5, v1
	v_mul_lo_u32 v3, v1, v2
	v_sub_u32_e32 v3, v5, v3
	v_add_u32_e32 v4, 1, v1
	v_cmp_ge_u32_e32 vcc, v3, v2
	s_nop 1
	v_cndmask_b32_e32 v1, v1, v4, vcc
	v_sub_u32_e32 v4, v3, v2
	v_cndmask_b32_e32 v3, v3, v4, vcc
	v_add_u32_e32 v4, 1, v1
	v_cmp_ge_u32_e32 vcc, v3, v2
	v_add_u32_e32 v3, 1, v5
	s_nop 0
	v_cndmask_b32_e32 v1, v1, v4, vcc
	v_mul_lo_u32 v4, v2, v1
	v_add_u32_e32 v2, v4, v2
	v_mul_lo_u32 v7, v1, v6
	v_cmp_ne_u32_e32 vcc, v3, v2
	s_mov_b32 s8, 0
	s_cbranch_vccnz .Lnb_loop_10
	buffer_wbl2 sc1
	v_mov_b32_e32 v8, 1
	v_mov_b32_e32 v9, 0x2404
	s_waitcnt vmcnt(0)
	global_atomic_add v9, v8, s[46:47]
	v_add_u32_e32 v9, 0x100, v9
	global_atomic_add v9, v8, s[46:47]
	v_add_u32_e32 v9, 0x100, v9
	global_atomic_add v9, v8, s[46:47]
	v_add_u32_e32 v9, 0x100, v9
	global_atomic_add v9, v8, s[46:47]
	v_add_u32_e32 v9, 0x100, v9
	global_atomic_add v9, v8, s[46:47]
	v_add_u32_e32 v9, 0x100, v9
	global_atomic_add v9, v8, s[46:47]
	v_add_u32_e32 v9, 0x100, v9
	global_atomic_add v9, v8, s[46:47]
	v_add_u32_e32 v9, 0x100, v9
	global_atomic_add v9, v8, s[46:47]
	v_add_u32_e32 v9, 0x100, v9
	global_atomic_add v9, v8, s[46:47]
	v_add_u32_e32 v9, 0x100, v9
	global_atomic_add v9, v8, s[46:47]
	v_add_u32_e32 v9, 0x100, v9
	global_atomic_add v9, v8, s[46:47]
	v_add_u32_e32 v9, 0x100, v9
	global_atomic_add v9, v8, s[46:47]
	v_add_u32_e32 v9, 0x100, v9
	global_atomic_add v9, v8, s[46:47]
	v_add_u32_e32 v9, 0x100, v9
	global_atomic_add v9, v8, s[46:47]
	v_add_u32_e32 v9, 0x100, v9
	global_atomic_add v9, v8, s[46:47]
	v_add_u32_e32 v9, 0x100, v9
	global_atomic_add v9, v8, s[46:47]

; #define PG8_STAGE(bufoff, gbase, voff) do { _Pragma("unroll") for (int _i = 0; _i < 2; ++_i) \
;         __builtin_amdgcn_global_load_lds((const unsigned*)((const char*)(gbase) + (voff)[_i]), (PG8_LAS unsigned*)(lds + (bufoff) + ldsw + _i * 8192), 16, 0, 0); } while (0)
; #define PG8_WAIT_V(n) asm volatile("s_waitcnt vmcnt(" #n ")" ::: "memory")
; #define PG8_BAR __builtin_amdgcn_s_barrier()
;     ...
;     for (int i = 0; i < 2; ++i) { int R, C; stage_rc(tid * 16 + i * 8192, R, C); const int Rb = Epi::PERM ? ((R & ~31) + perm32(R & 31)) : R;
;         const int Ra = AMODE ? (62 * (R >> 6) + (R & 63)) : R; voffA[i] = (unsigned)(Ra * K + C) * 2u; voffB[i] = (unsigned)(Rb * K + C) * 2u; }
;     const size_t kstep = (size_t)(BK * 2);
;     const size_t hstepB = (size_t)HALF * K * 2; const size_t hstepA = (size_t)(AMODE ? 124 : HALF) * K * 2;
;     const size_t tstepB = 2 * hstepB; const size_t tstepA = 2 * hstepA;
;     const unsigned ldsw = (unsigned)wid * 1024u;
;     const int aoff = lds_byte(wr * 64 + fr, fq * 8), boff = lds_byte(wc * 32 + fr, fq * 8);
;     ...
;     Unit cur, nxt; int ui = 0;
;     if (!S.next(0, cur)) return;
;     f32x4 acc[2][2][4][2];
; #pragma unroll
;     for (int a = 0; a < 2; ++a)
; #pragma unroll
;         for (int b = 0; b < 2; ++b)
; #pragma unroll
;             for (int m = 0; m < 4; ++m)
; #pragma unroll
;                 for (int n = 0; n < 2; ++n) acc[a][b][m][n] = (f32x4){0.f, 0.f, 0.f, 0.f};
;     bf16x8 At[4][2], B0[2][2], B1[2][2];
;     const char* cA = (const char*)g.A + (size_t)cur.pm * tstepA; const char* cB = (const char*)g.Bt + (size_t)cur.pn * tstepB;
;     S.a_ready(cur);
;     if constexpr (SP2) {
;         PG8_STAGE(PG8_SB(0, 0), cB, voffB); PG8_STAGE(PG8_SB(0, 1), cB + hstepB, voffB); PG8_STAGE(PG8_SA(0, 0), cA, voffA); PG8_STAGE(PG8_SA(0, 1), cA + hstepA, voffA);
;         if (wr == 1) PG8_BAR;
;         PG8_WAIT_V(2); PG8_BAR;
;         PG8_STAGE(PG8_SB(1, 0), cB + kstep, voffB); PG8_STAGE(PG8_SA(1, 0), cA + kstep, voffA); PG8_STAGE(PG8_SB(1, 1), cB + hstepB + kstep, voffB);
.Lnb_done_10:
	s_waitcnt vmcnt(0)
.LBB0_882:
	s_or_b64 exec, exec, s[0:1]
	v_readlane_b32 s4, v253, 42
	v_mov_b32_e32 v12, v186
	v_readlane_b32 s5, v253, 43
	s_waitcnt lgkmcnt(0)
	s_barrier
	s_and_b64 vcc, exec, s[4:5]
	v_readfirstlane_b32 s0, v12
	s_cbranch_vccz .LBB0_906
	v_lshlrev_b32_e32 v0, 4, v12
	v_add_u32_e32 v1, 0x2000, v0
	v_ashrrev_i32_e32 v2, 31, v1
	v_lshrrev_b32_e32 v2, 22, v2
	v_add_u32_e32 v2, v1, v2
	v_ashrrev_i32_e32 v4, 10, v2
	v_mul_i32_i24_e32 v2, 0x400, v4
	v_sub_u32_e32 v1, v1, v2
	v_lshrrev_b32_e32 v2, 4, v1
	v_bitop3_b32 v1, v2, v1, 32 bitop3:0x6c
	v_ashrrev_i32_e32 v2, 31, v1
	v_lshrrev_b32_e32 v2, 26, v2
	v_add_u32_e32 v2, v1, v2
	v_ashrrev_i32_e32 v5, 6, v2
	v_and_b32_e32 v2, 0xc0, v2
	v_sub_u32_e32 v1, v1, v2
	v_ashrrev_i16_sdwa v1, v191, sext(v1) dst_sel:DWORD dst_unused:UNUSED_PAD src0_sel:DWORD src1_sel:BYTE_0
	v_bfe_i32 v7, v1, 0, 16
	v_bfe_i32 v1, v12, 27, 1
	v_lshrrev_b32_e32 v1, 22, v1
	v_add_u32_e32 v1, v0, v1
	v_and_b32_e32 v1, 0xfffffc00, v1
	v_sub_u32_e32 v0, v0, v1
	v_lshrrev_b32_e32 v1, 4, v0
	v_ashrrev_i32_e32 v2, 31, v12
	v_bitop3_b32 v0, v1, v0, 32 bitop3:0x6c
	v_lshrrev_b32_e32 v2, 26, v2
	v_readlane_b32 s4, v254, 61
	v_ashrrev_i32_e32 v1, 31, v0
	v_add_u32_e32 v2, v12, v2
	v_readlane_b32 s5, v254, 62
	v_lshlrev_b32_e32 v3, 3, v4
	v_lshrrev_b32_e32 v1, 26, v1
	v_ashrrev_i32_e32 v9, 6, v2
	s_and_b64 s[4:5], s[4:5], exec
	s_mov_b32 s1, 0x2a00000
	v_and_b32_e32 v3, 0xfffff0, v3
	v_add_u32_e32 v1, v0, v1
	v_lshlrev_b32_e32 v2, 3, v9
	s_cselect_b32 s1, s1, 0x3000000
	v_add_u32_e32 v3, v5, v3
	s_movk_i32 s2, 0xb00
	v_lshlrev_b32_e32 v6, 5, v4
	v_ashrrev_i32_e32 v8, 6, v1
	v_and_b32_e32 v2, 0xfffff0, v2
	s_add_u32 s20, s46, s1
	v_mul_lo_u32 v3, v3, s2
	v_and_b32_e32 v6, 32, v6
	v_add_u32_e32 v2, v8, v2
	s_addc_u32 s21, s47, 0
	s_ashr_i32 s1, s0, 6
	v_or_b32_e32 v3, v3, v6
	v_mul_lo_u32 v2, v2, s2
	v_and_b32_e32 v1, 0xc0, v1
	v_readlane_b32 s2, v254, 17
	s_ashr_i32 s4, s0, 8
	s_lshl_b32 s22, s1, 10
	v_add_lshl_u32 v128, v3, v7, 1
	v_lshlrev_b32_e32 v3, 5, v9
	v_sub_u32_e32 v0, v0, v1
	s_mul_i32 s5, s2, 0x160000
	v_and_b32_e32 v10, 32, v3
	v_ashrrev_i16_sdwa v0, v191, sext(v0) dst_sel:DWORD dst_unused:UNUSED_PAD src0_sel:DWORD src1_sel:BYTE_0
	s_add_u32 s14, s20, s5
	s_mul_hi_i32 s5, s2, 0x160000
	v_or_b32_e32 v2, v2, v10
	v_bfe_i32 v11, v0, 0, 16
	s_addc_u32 s15, s21, s5
	s_add_i32 s23, s22, 0
	v_add_lshl_u32 v160, v2, v11, 1
	s_add_i32 m0, s23, 0x10000
	s_load_dword s27, s[70:71], 0x0
	global_load_lds_dwordx4 v160, s[14:15]
	s_add_i32 m0, s23, 0x12000
	s_add_u32 s6, s14, 0xb0000
	global_load_lds_dwordx4 v128, s[14:15]
	s_addc_u32 s7, s15, 0
	s_add_i32 m0, s23, 0x14000
	s_add_i32 s24, s23, 0x2000
	global_load_lds_dwordx4 v160, s[6:7]
	s_add_i32 m0, s23, 0x16000
	s_add_i32 s25, s23, 0x4000
	global_load_lds_dwordx4 v128, s[6:7]
	v_readlane_b32 s6, v254, 28
	s_mov_b32 m0, s23
	v_readlane_b32 s7, v254, 29
	s_add_i32 s26, s23, 0x6000
	v_mov_b32_e32 v129, v161
	s_cmp_eq_u32 s4, 1
	v_lshl_add_u64 v[0:1], s[14:15], 0, v[160:161]
	v_lshl_add_u64 v[2:3], s[14:15], 0, v[128:129]
	global_load_lds_dwordx4 v160, s[6:7]
	s_mov_b32 m0, s24
	s_nop 0
	global_load_lds_dwordx4 v128, s[6:7]
	v_readlane_b32 s6, v254, 30
	s_mov_b32 m0, s25
	v_readlane_b32 s7, v254, 31
	s_nop 4
	global_load_lds_dwordx4 v160, s[6:7]
	s_mov_b32 m0, s26
	s_nop 0
	global_load_lds_dwordx4 v128, s[6:7]
	s_cselect_b64 s[6:7], -1, 0
	s_cmp_lg_u32 s4, 1
	s_cbranch_scc1 .LBB0_885
	s_barrier

; __device__ __forceinline__ unsigned xb_ld(unsigned* p)              { return __hip_atomic_load(p, __ATOMIC_RELAXED, __HIP_MEMORY_SCOPE_AGENT); }
; __device__ __forceinline__ unsigned xb_add(unsigned* p, unsigned v) { return __hip_atomic_fetch_add(p, v, __ATOMIC_RELAXED, __HIP_MEMORY_SCOPE_AGENT); }
; #define XB_SPIN(cond, bar) do { unsigned _sp = 0; while (cond) { __builtin_amdgcn_s_sleep(1); \
;     if ((++_sp & 255u) == 0u) { if (xb_ld(&(bar)[XB_TMO])) break; if (_sp > XB_SPIN_CAP) { atomicAdd(&(bar)[XB_TMO], 1u); break; } } } } while (0)
; #define GSYNC() do { XcdBarrier b_; b_.bar = (unsigned*)args.ws; b_.x = xb_xcc_id(); b_.st = (volatile LAS unsigned*)((LAS unsigned char*)lds + LDS_BYTES - 64) + 8; xcd_barrier(b_); if constexpr ((DUP) & 0x10000) xcd_barrier(b_); } while (0)
; __device__ __forceinline__ void xcd_barrier(const XcdBarrier& b) {
;     asm volatile("s_waitcnt vmcnt(0)" ::: "memory");
;     __syncthreads();
;     if (threadIdx.x == 0) {
;         unsigned* bar = b.bar;
;         __builtin_amdgcn_s_waitcnt(0);
;         unsigned nloc = b.st[0], nx = b.st[1];
;         if (nloc == 0u) { xcd_barrier_complete(bar, b.x, nloc, nx); b.st[0] = nloc; b.st[1] = nx; }
;         const unsigned old = xb_add(&bar[XB_XSUB(b.x)], 1u);
;         const unsigned gen = old / nloc;
;         if (old + 1u == (gen + 1u) * nloc) {
;             __builtin_amdgcn_fence(__ATOMIC_RELEASE, "agent");
;             asm volatile("s_waitcnt vmcnt(0)" ::: "memory");
;             const unsigned og = xb_add(&bar[XB_TOP], 1u);
;             const unsigned tg = og / nx;
;             if (og + 1u == (tg + 1u) * nx) xb_add(&bar[XB_TOPGEN], 1u);
;             else XB_SPIN(xb_ld(&bar[XB_TOPGEN]) == tg, bar);
;             __builtin_amdgcn_fence(__ATOMIC_ACQUIRE, "agent");
;             xb_add(&bar[XB_XGEN(b.x)], 1u);
;             asm volatile("s_waitcnt vmcnt(0)" ::: "memory");
;         } else {
;             XB_SPIN(xb_ld(&bar[XB_XGEN(b.x)]) == gen, bar);
;             __builtin_amdgcn_fence(__ATOMIC_ACQUIRE, "agent");
;             asm volatile("s_waitcnt vmcnt(0)" ::: "memory");
;         }
;     }
;     __syncthreads();
; }
; __global__ void __launch_bounds__(NTHR, 2) fwd_megakernel(Args args) {
;     ...
;         if (even) {
;             GSYNC();
.LBB0_906:
	v_readlane_b32 s0, v254, 61
	v_readlane_b32 s1, v254, 62
	s_mov_b64 s[6:7], -1
	s_andn2_b64 vcc, exec, s[0:1]
	s_mov_b64 s[0:1], -1
	s_cbranch_vccnz .LBB0_118
	s_getreg_b32 s4, hwreg(HW_REG_XCC_ID, 0, 4)
	s_waitcnt vmcnt(0)
	s_barrier
	s_and_saveexec_b64 s[0:1], s[68:69]
	s_cbranch_execz .LBB0_959
	v_readlane_b32 s2, v254, 42
	s_waitcnt vmcnt(0) expcnt(0) lgkmcnt(0)
	buffer_inv sc1
	s_and_b32 s10, s4, 15
	s_lshl_b32 s5, s10, 8
	v_mov_b32_e32 v0, s2
	ds_read_b32 v2, v0
	v_readlane_b32 s2, v254, 43
	s_add_u32 s12, s46, s5
	s_addc_u32 s13, s47, 0
	v_mov_b32_e32 v3, 1
	v_mov_b32_e32 v0, s2
	ds_read_b32 v6, v0
	v_mov_b32_e32 v5, 0x1400
	s_waitcnt lgkmcnt(0)
	global_atomic_add v3, v5, v3, s[12:13] sc0
	v_cvt_f32_u32_e32 v4, v2
	s_waitcnt vmcnt(0)
	v_mov_b32_e32 v5, v3
	v_sub_u32_e32 v3, 0, v2
	v_rcp_iflag_f32_e32 v4, v4
	s_nop 0
	v_mul_f32_e32 v4, 0x4f7ffffe, v4
	v_cvt_u32_f32_e32 v4, v4
	v_mul_lo_u32 v1, v3, v4
	v_mul_hi_u32 v1, v4, v1
	v_add_u32_e32 v1, v4, v1
	v_mul_hi_u32 v1, v5, v1
	v_mul_lo_u32 v3, v1, v2
	v_sub_u32_e32 v3, v5, v3
	v_add_u32_e32 v4, 1, v1
	v_cmp_ge_u32_e32 vcc, v3, v2
	s_nop 1
	v_cndmask_b32_e32 v1, v1, v4, vcc
	v_sub_u32_e32 v4, v3, v2
	v_cndmask_b32_e32 v3, v3, v4, vcc
	v_add_u32_e32 v4, 1, v1
	v_cmp_ge_u32_e32 vcc, v3, v2
	v_add_u32_e32 v3, 1, v5
	s_nop 0
	v_cndmask_b32_e32 v1, v1, v4, vcc
	v_mul_lo_u32 v4, v2, v1
	v_add_u32_e32 v2, v4, v2
	v_mul_lo_u32 v7, v1, v6
	v_cmp_ne_u32_e32 vcc, v3, v2
	s_mov_b32 s8, 0
	s_cbranch_vccnz .Lnb_loop_11
	buffer_wbl2 sc1
	v_mov_b32_e32 v8, 1
	v_mov_b32_e32 v9, 0x2404
	s_waitcnt vmcnt(0)
	global_atomic_add v9, v8, s[46:47]
	v_add_u32_e32 v9, 0x100, v9
	global_atomic_add v9, v8, s[46:47]
	v_add_u32_e32 v9, 0x100, v9
	global_atomic_add v9, v8, s[46:47]
	v_add_u32_e32 v9, 0x100, v9
	global_atomic_add v9, v8, s[46:47]
	v_add_u32_e32 v9, 0x100, v9
	global_atomic_add v9, v8, s[46:47]
	v_add_u32_e32 v9, 0x100, v9
	global_atomic_add v9, v8, s[46:47]
	v_add_u32_e32 v9, 0x100, v9
	global_atomic_add v9, v8, s[46:47]
	v_add_u32_e32 v9, 0x100, v9
	global_atomic_add v9, v8, s[46:47]
	v_add_u32_e32 v9, 0x100, v9
	global_atomic_add v9, v8, s[46:47]
	v_add_u32_e32 v9, 0x100, v9
	global_atomic_add v9, v8, s[46:47]
	v_add_u32_e32 v9, 0x100, v9
	global_atomic_add v9, v8, s[46:47]
	v_add_u32_e32 v9, 0x100, v9
	global_atomic_add v9, v8, s[46:47]
	v_add_u32_e32 v9, 0x100, v9
	global_atomic_add v9, v8, s[46:47]
	v_add_u32_e32 v9, 0x100, v9
	global_atomic_add v9, v8, s[46:47]
	v_add_u32_e32 v9, 0x100, v9
	global_atomic_add v9, v8, s[46:47]
	v_add_u32_e32 v9, 0x100, v9
	global_atomic_add v9, v8, s[46:47]

; DI void norm_phase(const Ctx& c, const float* __restrict__ h, const float* __restrict__ g, bf16* __restrict__ xn) {
;     const f32x4* gr = (const f32x4*)g + c.lane;
;     f32x4 gg[4];
; #pragma unroll
;     for (int j = 0; j < 4; ++j) gg[j] = gr[64 * j];
;     for (int m0 = c.gw * 4; m0 < M; m0 += c.NGW * 4) {
;         f32x4 v[4][4];
; #pragma unroll
;         for (int r = 0; r < 4; ++r) { const f32x4* xr = (const f32x4*)(h + (size_t)(m0 + r) * D) + c.lane;
; #pragma unroll
;             for (int j = 0; j < 4; ++j) v[r][j] = __builtin_nontemporal_load(xr + 64 * j); }
; #pragma unroll
;         for (int r = 0; r < 4; ++r) {
;             float s = 0.f;
; #pragma unroll
;             for (int j = 0; j < 4; ++j) s += (v[r][j].x * v[r][j].x + v[r][j].y * v[r][j].y) + (v[r][j].z * v[r][j].z + v[r][j].w * v[r][j].w);
;             const float rstd = 1.f / sqrtf(wave_sum(s) * (1.f / 1024.f) + 1e-6f);
; __global__ void __launch_bounds__(NTHR, 2) fwd_megakernel(Args args) {
;     ...
;             norm_phase(mkctx(lds), H, args.in[1] + 1024, XN);
.Lnb_done_11:
	s_waitcnt vmcnt(0)
.LBB0_959:
	s_or_b64 exec, exec, s[0:1]
	s_waitcnt lgkmcnt(0)
	v_mov_b32_e32 v0, v186
	s_barrier
	s_load_dword s14, s[70:71], 0x0
	v_readfirstlane_b32 s0, v0
	s_ashr_i32 s0, s0, 6
	s_add_i32 s0, s0, s72
	s_cmpk_gt_i32 s0, 0x1fff
	s_cbranch_scc1 .LBB0_962
	v_and_b32_e32 v16, 63, v0
	v_readlane_b32 s4, v254, 14
	v_lshlrev_b32_e32 v160, 4, v16
	v_readlane_b32 s5, v254, 15
	s_nop 4
	global_load_dwordx4 v[0:3], v160, s[4:5] offset:3072
	global_load_dwordx4 v[4:7], v160, s[4:5] offset:2048
	global_load_dwordx4 v[8:11], v160, s[4:5] offset:1024
	global_load_dwordx4 v[12:15], v160, s[4:5]
	v_and_b32_e32 v17, 64, v193
	v_add_u32_e32 v17, 64, v17
	v_xor_b32_e32 v18, 1, v193
	v_cmp_lt_i32_e32 vcc, v18, v17
	s_lshl_b32 s8, s0, 2
	s_ashr_i32 s9, s8, 31
	v_cndmask_b32_e32 v18, v193, v18, vcc
	v_lshlrev_b32_e32 v81, 2, v18
	v_xor_b32_e32 v18, 2, v193
	v_cmp_lt_i32_e32 vcc, v18, v17
	s_waitcnt lgkmcnt(0)
	s_lshl_b32 s4, s14, 5
	s_lshl_b64 s[0:1], s[8:9], 11
	v_cndmask_b32_e32 v18, v193, v18, vcc
	v_lshlrev_b32_e32 v84, 2, v18
	v_xor_b32_e32 v18, 4, v193
	v_cmp_lt_i32_e32 vcc, v18, v17
	v_readlane_b32 s2, v254, 38
	s_add_u32 s0, s2, s0
	v_cndmask_b32_e32 v18, v193, v18, vcc
	v_lshlrev_b32_e32 v85, 2, v18
	v_xor_b32_e32 v18, 8, v193
	v_cmp_lt_i32_e32 vcc, v18, v17
	v_readlane_b32 s2, v254, 39
	v_lshlrev_b32_e32 v16, 3, v16
	v_cndmask_b32_e32 v18, v193, v18, vcc
	v_lshlrev_b32_e32 v86, 2, v18
	v_xor_b32_e32 v18, 16, v193
	v_cmp_lt_i32_e32 vcc, v18, v17
	s_addc_u32 s1, s2, s1
	s_ashr_i32 s5, s4, 31
	v_cndmask_b32_e32 v18, v193, v18, vcc
	v_lshlrev_b32_e32 v87, 2, v18
	v_xor_b32_e32 v18, 32, v193
	v_cmp_lt_i32_e32 vcc, v18, v17
	s_lshl_b64 s[10:11], s[4:5], 11
	v_readlane_b32 s2, v254, 40
	v_cndmask_b32_e32 v17, v193, v18, vcc
	v_lshlrev_b32_e32 v88, 2, v17
	v_mov_b32_e32 v17, v161
	v_lshl_add_u64 v[76:77], s[0:1], 0, v[16:17]
	s_lshl_b64 s[0:1], s[8:9], 12
	s_add_u32 s0, s2, s0
	v_readlane_b32 s2, v254, 41
	s_addc_u32 s1, s2, s1
	v_lshl_add_u64 v[78:79], s[0:1], 0, v[160:161]
	s_lshl_b64 s[12:13], s[4:5], 12
	s_movk_i32 s2, 0xf000

; #define GSYNC() do { XcdBarrier b_; b_.bar = (unsigned*)args.ws; b_.x = xb_xcc_id(); b_.st = (volatile LAS unsigned*)((LAS unsigned char*)lds + LDS_BYTES - 64) + 8; xcd_barrier(b_); if constexpr ((DUP) & 0x10000) xcd_barrier(b_); } while (0)
; __global__ void __launch_bounds__(NTHR, 2) fwd_megakernel(Args args) {
;     ...
;             GSYNC();
;             norm_phase(mkctx(lds), H, args.in[1] + 1024, XN);
;             GSYNC();
;         }
;     }
.Lnb_done_12:
	s_waitcnt vmcnt(0)
	s_branch .LBB0_117
